# out-projection (E3, O4): the residual tile's cache lines are touched from inside the k-loop, 8 rows per k-step over the preceding 8 iterations (one extra masked load per half-step, counted waits adjus
# speedup vs baseline: 1.0086x; 1.0086x over previous
;     ...
;   if (bid < ntiles) {
;     const int my_tiles = (ntiles - 1 - bid) / G + 1;
;     const int last_id = bid + (my_tiles - 1) * G;
;     const int S = my_tiles * nk;
;     f32x4 acc[4][TI];
; #pragma unroll
;     for (int a = 0; a < 4; ++a)
; #pragma unroll
;       for (int b = 0; b < TI; ++b) acc[a][b] = (f32x4){0.f, 0.f, 0.f, 0.f};
;     u32x4 ra0[4], rb0[2], ra1[4], rb1[2];
;     u32x4 rx0 = (u32x4){0u, 0u, 0u, 0u}, rx1 = (u32x4){0u, 0u, 0u, 0u};
;     float ss[5] = {0.f, 0.f, 0.f, 0.f, 0.f};
;     int l_id = bid, l_kt = 0, c_id = bid, c_kt = 0, st_kt = 0;
;     const int srow = tid >> 3;
;     const int soff = srow * 128 + (((tid & 7) ^ (srow & 7)) << 4);
;     const int wrow = tid5 >> 3;
;     const int woff = wrow * 128 + (((tid5 & 7) ^ (wrow & 7)) << 4);
;     ...
; #pragma unroll 1
;     for (int s = 0; s < S; s += 2) {
.LBB0_936:
	s_or_b64 exec, exec, s[6:7]
	s_lshl_b32 s31, s8, 4
	s_add_i32 s31, s31, 16
	s_cmp_lt_i32 s31, 1
	s_waitcnt lgkmcnt(0)
	s_barrier
	s_cbranch_scc1 .LBB0_983
	v_and_b32_e32 v32, 15, v13
	v_bfe_u32 v15, v13, 6, 1
	v_lshlrev_b32_e32 v36, 7, v32
	v_ashrrev_i32_e32 v14, 7, v13
	v_lshl_or_b32 v37, v15, 13, v36
	v_lshrrev_b32_e32 v34, 4, v13
	v_bfe_u32 v35, v13, 4, 2
	v_add_u32_e32 v179, s9, v37
	v_lshl_or_b32 v180, v14, 13, v36
	v_and_b32_e32 v36, 7, v13
	v_and_b32_e32 v37, 64, v13
	v_bitop3_b32 v34, v34, v36, 3 bitop3:0x6c
	v_cmp_ne_u32_e64 s[40:41], 0, v37
	v_or_b32_e32 v37, 4, v35
	v_bitop3_b32 v36, v35, v36, 4 bitop3:0x36
	v_lshlrev_b32_e32 v13, 4, v13
	v_lshlrev_b32_e32 v181, 4, v34
	v_lshlrev_b32_e32 v34, 4, v35
	v_lshlrev_b32_e32 v182, 4, v36
	v_lshlrev_b32_e32 v36, 4, v37
	v_and_b32_e32 v37, 0x70, v13
	v_lshlrev_b32_e32 v183, 6, v14
	v_lshl_or_b32 v184, v15, 6, v32
	v_or_b32_e32 v13, v15, v32
	v_mov_b32_e32 v14, v12
	v_mov_b32_e32 v15, v12
	s_add_u32 s52, s44, 0x2040000
	v_cmp_eq_u32_e32 vcc, 0, v32
	v_lshlrev_b32_e32 v172, 2, v35
	v_cmp_eq_u32_e64 s[42:43], 0, v13
	v_mov_b32_e32 v13, v12
	v_mov_b32_e32 v68, 0
	v_add_u32_e32 v185, v33, v34
	v_add_u32_e32 v201, v33, v36
	v_add_u32_e32 v202, v33, v37
	v_mov_b64_e32 v[34:35], v[14:15]
	v_mov_b64_e32 v[38:39], v[14:15]
	v_mov_b64_e32 v[90:91], v[14:15]
	v_mov_b64_e32 v[110:111], v[14:15]
	s_addc_u32 s53, s45, 0
	s_mov_b32 s49, 0
	s_mov_b32 s6, 2
	s_and_b64 s[54:55], vcc, s[40:41]
	v_mov_b64_e32 v[32:33], v[12:13]
	v_mov_b64_e32 v[36:37], v[12:13]
	v_mov_b64_e32 v[88:89], v[12:13]
	v_mov_b64_e32 v[108:109], v[12:13]
	s_mov_b32 s8, 0
	s_mov_b32 s7, s12
	v_mov_b32_e32 v69, v68
	v_mov_b32_e32 v70, v68
	v_mov_b32_e32 v71, v68
	v_mov_b32_e32 v72, v68
	v_mov_b32_e32 v73, v68
	v_mov_b32_e32 v74, v68
	v_mov_b32_e32 v75, v68
	v_mov_b32_e32 v76, v68
	v_mov_b32_e32 v77, v68
	v_mov_b32_e32 v78, v68
	v_mov_b32_e32 v79, v68
	v_mov_b32_e32 v80, v68
	v_mov_b32_e32 v81, v68
	v_mov_b32_e32 v82, v68
	v_mov_b32_e32 v83, v68
	v_mov_b32_e32 v84, v68
	v_mov_b32_e32 v85, v68
	v_mov_b32_e32 v86, v68
	v_mov_b32_e32 v87, v68
	v_mov_b32_e32 v92, v68
	v_mov_b32_e32 v93, v68
	v_mov_b32_e32 v94, v68
	v_mov_b32_e32 v95, v68
	v_mov_b32_e32 v96, v68
	v_mov_b32_e32 v97, v68
	v_mov_b32_e32 v98, v68
	v_mov_b32_e32 v99, v68
	v_mov_b32_e32 v100, v68
	v_mov_b32_e32 v101, v68
	v_mov_b32_e32 v102, v68
	v_mov_b32_e32 v103, v68
	v_mov_b32_e32 v104, v68
	v_mov_b32_e32 v105, v68
	v_mov_b32_e32 v106, v68
	v_mov_b32_e32 v107, v68
	v_mov_b32_e32 v112, v68
	v_mov_b32_e32 v113, v68
	v_mov_b32_e32 v114, v68
	v_mov_b32_e32 v115, v68
	v_mov_b32_e32 v116, v68
	v_mov_b32_e32 v117, v68
	v_mov_b32_e32 v118, v68
	v_mov_b32_e32 v119, v68
	v_mov_b32_e32 v120, v68
	v_mov_b32_e32 v121, v68
	v_mov_b32_e32 v122, v68
	v_mov_b32_e32 v123, v68
	v_mov_b32_e32 v124, v68
	v_mov_b32_e32 v125, v68
	v_mov_b32_e32 v126, v68
	v_mov_b32_e32 v127, v68
	v_mov_b32_e32 v128, v68
	v_mov_b32_e32 v129, v68
	v_mov_b32_e32 v130, v68
	v_mov_b32_e32 v131, v68
	v_mov_b32_e32 v132, v68
	v_mov_b32_e32 v133, v68
	v_mov_b32_e32 v134, v68
	v_mov_b32_e32 v135, v68
	v_mov_b32_e32 v136, v68
	v_mov_b32_e32 v137, v68
	v_mov_b32_e32 v138, v68
	v_mov_b32_e32 v139, v68
	s_lshr_b32 s100, s12, 6
	s_lshl_b32 s100, s100, 3
	s_and_b32 s101, s12, 7
	s_or_b32 s100, s100, s101
	s_mulk_i32 s100, 0x102
	s_add_i32 s100, s100, s30
	s_lshl_b32 s100, s100, 11
	s_bfe_u32 s101, s12, 0x30003
	s_lshl_b32 s101, s101, 8
	s_add_i32 s100, s100, s101
	v_mbcnt_lo_u32_b32 v251, -1, 0
	v_mbcnt_hi_u32_b32 v251, -1, v251
	v_and_b32_e32 v251, 7, v251
	v_and_b32_e32 v250, 64, v184
	v_add_u32_e32 v251, v250, v251
	v_lshlrev_b32_e32 v250, 1, v183
	v_lshl_add_u32 v251, v251, 11, v250
	global_load_dword v249, v12, s[52:53]
	s_branch .LBB0_939

; #define MFMA16(a, b, c) __builtin_amdgcn_mfma_f32_16x16x32_bf16((a), (b), (c), 0, 0, 0)
;     ...
;     auto issue = [&](u32x4 (&ra)[4], u32x4 (&rb)[2], u32x4& rx) {
;       const int idc = l_id < last_id ? l_id : last_id;
;       int mt, nt; if (TMAP == 1) rem_tile(idc, mt, nt); else tile_of(idc, ntn, mt, nt);
;       const bf16_t* A = (l_kt < ktsplit) ? A0 : A1;
;       const int kk = (l_kt < ktsplit) ? l_kt : l_kt - ktsplit;
;       const int arow = mt * 2 * BMH + hh * BMH + srow;
;       const bf16_t* akb = A + kk * kstride + (tid & 7) * 8;
;       const bf16_t* wp = W + (size_t)(nt * 128 + wrow) * K + l_kt * 64 + (tid5 & 7) * 8;
; #pragma unroll
;       for (int i = 0; i < 4; ++i) {
;         int r = arow + 32 * i; r = r < M_ ? r : M_ - 1;
;         ra[i] = *(const u32x4*)(akb + (size_t)r * lda);
;       }
; #pragma unroll
;       for (int i = 0; i < 2; ++i) rb[i] = *(const u32x4*)(wp + (size_t)i * 64 * K);
;       if (TI == 5) rx = *(const u32x4*)(akb + (size_t)(arow - srow + 128) * lda);
;       if (++l_kt == nk) { l_kt = 0; l_id += G; }
;     };
;     ...
;     auto compute = [&](int buf) {
;       const unsigned char* Ab = As + buf * ASTG + (wn * 64 + lr) * 128;
;       const unsigned char* Ax = Ax0 + buf * 128;
;       const unsigned char* Bb = Bs + buf * 16384 + (wm * 64 + lr) * 128;
; #pragma unroll
;       for (int ks = 0; ks < 2; ++ks) {
;         if (TI == 5 && ks == 1) __builtin_amdgcn_sched_barrier(0);
;         const int sw = ((ks * 4 + lq) ^ (lr & 7)) << 4;
;         bf16x8 wf[4], xf[TI];
; #pragma unroll
;         for (int i = 0; i < 4; ++i) {
;           wf[i] = *(const bf16x8*)(Bb + i * 2048 + sw);
;           xf[i] = *(const bf16x8*)(Ab + i * 2048 + sw);
;         }
;         if (TI == 5) xf[TI - 1] = *(const bf16x8*)(Ax + ((ks * 4 + lq) << 4));
; #pragma unroll
;         for (int ni = 0; ni < 4; ++ni)
; #pragma unroll
;           for (int ti = 0; ti < 4; ++ti) acc[ni][ti] = MFMA16(wf[ni], xf[ti], acc[ni][ti]);
;         if (TI == 5) {
;           if (wn == 0) { acc[0][TI - 1] = MFMA16(wf[0], xf[TI - 1], acc[0][TI - 1]); acc[1][TI - 1] = MFMA16(wf[1], xf[TI - 1], acc[1][TI - 1]); }
;           else { acc[2][TI - 1] = MFMA16(wf[2], xf[TI - 1], acc[2][TI - 1]); acc[3][TI - 1] = MFMA16(wf[3], xf[TI - 1], acc[3][TI - 1]); }
;         }
;       }
.LBB0_943:
	v_add_u32_e32 v13, v180, v181
	ds_read_b128 v[148:151], v13 offset:32768
	s_cmp_lt_i32 s6, 2.0
	v_add_u32_e32 v14, s4, v176
	s_mul_i32 s4, s6, 0x60
	s_cselect_b32 s10, s47, 0
	s_cselect_b32 s11, s46, 0
	v_add_u32_e32 v15, v179, v181
	s_ashr_i32 s5, s4, 31
	s_waitcnt vmcnt(8)
	ds_read_b128 v[56:59], v15
	ds_read_b128 v[152:155], v13 offset:34816
	ds_read_b128 v[160:163], v15 offset:2048
	s_lshl_b64 s[4:5], s[4:5], 1
	ds_read_b128 v[204:207], v15 offset:4096
	s_add_u32 s4, s11, s4
	s_addc_u32 s5, s10, s5
	v_mov_b32_e32 v169, v12
	v_min_i32_e32 v42, 0x405f, v14
	v_lshl_add_u64 v[212:213], s[4:5], 0, v[168:169]
	v_min_i32_e32 v40, 0x407f, v14
	v_add_u32_e32 v42, 32, v42
	v_mad_i64_i32 v[40:41], s[10:11], v40, s83, v[212:213]
	v_mad_i64_i32 v[44:45], s[10:11], v42, s83, v[212:213]
	ds_read_b128 v[208:211], v15 offset:6144
	s_waitcnt lgkmcnt(1)
	v_mfma_f32_16x16x32_bf16 v[140:143], v[148:151], v[204:207], v[128:131]
	v_lshl_add_u32 v60, s9, 7, v174
	v_ashrrev_i32_e32 v61, 31, v60
	s_lshl_b32 s4, s6, 6
	ds_read_b128 v[128:131], v13 offset:36864
	global_load_dwordx4 v[40:43], v[40:41], off
	s_nop 0
	global_load_dwordx4 v[44:47], v[44:45], off
	ds_read_b128 v[156:159], v13 offset:38912
	v_lshlrev_b64 v[60:61], 11, v[60:61]
	s_ashr_i32 s5, s4, 31
	v_lshl_add_u64 v[60:61], s[50:51], 0, v[60:61]
	v_lshl_add_u64 v[60:61], s[4:5], 1, v[60:61]
	v_mov_b32_e32 v171, v12
	v_min_i32_e32 v48, 0x403f, v14
	v_min_i32_e32 v50, 0x401f, v14
	v_lshl_add_u64 v[60:61], v[60:61], 0, v[170:171]
	v_sub_u32_e32 v14, v14, v173
	v_add_u32_e32 v48, 64, v48
	v_add_u32_e32 v50, 0x60, v50
	v_add_co_u32_e32 v64, vcc, s2, v60
	v_add_u32_e32 v14, 0x80, v14
	v_mfma_f32_16x16x32_bf16 v[136:139], v[148:151], v[56:59], v[136:139]
	v_mad_i64_i32 v[48:49], s[10:11], v48, s83, v[212:213]
	v_mad_i64_i32 v[52:53], s[10:11], v50, s83, v[212:213]
	v_mfma_f32_16x16x32_bf16 v[120:123], v[152:155], v[56:59], v[120:123]
	v_addc_co_u32_e32 v65, vcc, 0, v61, vcc
	global_load_dwordx4 v[48:51], v[48:49], off
	s_nop 0
	global_load_dwordx4 v[52:55], v[52:53], off
	s_waitcnt lgkmcnt(1)
	v_mfma_f32_16x16x32_bf16 v[144:147], v[128:131], v[56:59], v[100:103]
	global_load_dwordx4 v[60:63], v[60:61], off
	s_nop 0
	global_load_dwordx4 v[64:67], v[64:65], off
	ds_read_b128 v[100:103], v185
	s_waitcnt lgkmcnt(1)
	v_mfma_f32_16x16x32_bf16 v[80:83], v[156:159], v[56:59], v[80:83]
	v_mad_i64_i32 v[56:57], s[4:5], v14, s83, v[212:213]
	global_load_dwordx4 v[56:59], v[56:57], off
	s_sub_u32 s101, s8, 0
	s_lshr_b32 s101, s101, 1
	s_lshl_b32 s101, s101, 14
	s_add_u32 s101, s101, s100
	v_add_u32_e32 v250, s101, v251
	s_sub_u32 s101, s8, 0
	s_cmp_le_u32 s101, 14
	s_cselect_b32 s101, -1, 0
	v_and_b32_e32 v250, s101, v250
	global_load_dword v249, v250, s[44:45]
	v_mfma_f32_16x16x32_bf16 v[132:135], v[148:151], v[160:163], v[132:135]
	v_mfma_f32_16x16x32_bf16 v[124:127], v[148:151], v[208:211], v[124:127]
	v_mfma_f32_16x16x32_bf16 v[116:119], v[152:155], v[160:163], v[116:119]
	v_mfma_f32_16x16x32_bf16 v[112:115], v[152:155], v[204:207], v[112:115]
	v_mfma_f32_16x16x32_bf16 v[104:107], v[152:155], v[208:211], v[104:107]
	v_mfma_f32_16x16x32_bf16 v[96:99], v[128:131], v[160:163], v[96:99]
	v_mfma_f32_16x16x32_bf16 v[92:95], v[128:131], v[204:207], v[92:95]
	v_mfma_f32_16x16x32_bf16 v[84:87], v[128:131], v[208:211], v[84:87]
	v_mfma_f32_16x16x32_bf16 v[76:79], v[156:159], v[160:163], v[76:79]
	v_mfma_f32_16x16x32_bf16 v[72:75], v[156:159], v[204:207], v[72:75]
	v_mfma_f32_16x16x32_bf16 v[68:71], v[156:159], v[208:211], v[68:71]
	s_and_saveexec_b64 s[4:5], s[40:41]
	s_xor_b64 s[4:5], exec, s[4:5]
	s_cbranch_execz .LBB0_945
	s_waitcnt lgkmcnt(0)
	v_mfma_f32_16x16x32_bf16 v[36:39], v[128:131], v[100:103], v[36:39]
	v_mfma_f32_16x16x32_bf16 v[32:35], v[156:159], v[100:103], v[32:35]

;     ...
;     auto store = [&](const u32x4 (&ra)[4], const u32x4 (&rb)[2], const u32x4& rx, int buf) {
; #pragma unroll
;       for (int i = 0; i < 4; ++i) {
;         if (RS) ss[i] += sumsq8(__builtin_bit_cast(bf16x8, ra[i]));
;         *(u32x4*)(As + buf * ASTG + i * 4096 + soff) = ra[i];
;       }
; #pragma unroll
;       for (int i = 0; i < 2; ++i) *(u32x4*)(Bs + buf * 16384 + i * 8192 + woff) = rb[i];
;       if (TI == 5) {
;         if (RS) ss[4] += sumsq8(__builtin_bit_cast(bf16x8, rx));
;         if (srow == 0) *(u32x4*)(Ax0 + buf * 128 + ((tid & 7) << 4)) = rx;
;       }
.LBB0_951:
	s_or_b64 exec, exec, s[4:5]
	s_waitcnt vmcnt(15)
	ds_write_b128 v178, v[0:3] offset:16384
	s_waitcnt vmcnt(14)
	ds_write_b128 v178, v[4:7] offset:20480
	s_waitcnt vmcnt(13)
	ds_write_b128 v178, v[8:11] offset:24576
	s_waitcnt vmcnt(12)
	ds_write_b128 v178, v[16:19] offset:28672
	s_waitcnt vmcnt(11)
	ds_write_b128 v177, v[20:23] offset:49152
	s_waitcnt vmcnt(10)
	ds_write_b128 v177, v[24:27] offset:57344
	s_and_saveexec_b64 s[4:5], s[38:39]
	s_cbranch_execz .LBB0_953
	s_waitcnt vmcnt(9)
	ds_write_b128 v202, v[28:31] offset:128

; #define MFMA16(a, b, c) __builtin_amdgcn_mfma_f32_16x16x32_bf16((a), (b), (c), 0, 0, 0)
;     ...
;     auto issue = [&](u32x4 (&ra)[4], u32x4 (&rb)[2], u32x4& rx) {
;       const int idc = l_id < last_id ? l_id : last_id;
;       int mt, nt; if (TMAP == 1) rem_tile(idc, mt, nt); else tile_of(idc, ntn, mt, nt);
;       const bf16_t* A = (l_kt < ktsplit) ? A0 : A1;
;       const int kk = (l_kt < ktsplit) ? l_kt : l_kt - ktsplit;
;       const int arow = mt * 2 * BMH + hh * BMH + srow;
;       const bf16_t* akb = A + kk * kstride + (tid & 7) * 8;
;       const bf16_t* wp = W + (size_t)(nt * 128 + wrow) * K + l_kt * 64 + (tid5 & 7) * 8;
; #pragma unroll
;       for (int i = 0; i < 4; ++i) {
;         int r = arow + 32 * i; r = r < M_ ? r : M_ - 1;
;         ra[i] = *(const u32x4*)(akb + (size_t)r * lda);
;       }
; #pragma unroll
;       for (int i = 0; i < 2; ++i) rb[i] = *(const u32x4*)(wp + (size_t)i * 64 * K);
;       if (TI == 5) rx = *(const u32x4*)(akb + (size_t)(arow - srow + 128) * lda);
;       if (++l_kt == nk) { l_kt = 0; l_id += G; }
;     };
;     ...
;     auto compute = [&](int buf) {
;       const unsigned char* Ab = As + buf * ASTG + (wn * 64 + lr) * 128;
;       const unsigned char* Ax = Ax0 + buf * 128;
;       const unsigned char* Bb = Bs + buf * 16384 + (wm * 64 + lr) * 128;
; #pragma unroll
;       for (int ks = 0; ks < 2; ++ks) {
;         if (TI == 5 && ks == 1) __builtin_amdgcn_sched_barrier(0);
;         const int sw = ((ks * 4 + lq) ^ (lr & 7)) << 4;
;         bf16x8 wf[4], xf[TI];
; #pragma unroll
;         for (int i = 0; i < 4; ++i) {
;           wf[i] = *(const bf16x8*)(Bb + i * 2048 + sw);
;           xf[i] = *(const bf16x8*)(Ab + i * 2048 + sw);
;         }
;         if (TI == 5) xf[TI - 1] = *(const bf16x8*)(Ax + ((ks * 4 + lq) << 4));
; #pragma unroll
;         for (int ni = 0; ni < 4; ++ni)
; #pragma unroll
;           for (int ti = 0; ti < 4; ++ti) acc[ni][ti] = MFMA16(wf[ni], xf[ti], acc[ni][ti]);
;         if (TI == 5) {
;           if (wn == 0) { acc[0][TI - 1] = MFMA16(wf[0], xf[TI - 1], acc[0][TI - 1]); acc[1][TI - 1] = MFMA16(wf[1], xf[TI - 1], acc[1][TI - 1]); }
;           else { acc[2][TI - 1] = MFMA16(wf[2], xf[TI - 1], acc[2][TI - 1]); acc[3][TI - 1] = MFMA16(wf[3], xf[TI - 1], acc[3][TI - 1]); }
;         }
;       }
;     };
.LBB0_957:
	s_and_b64 s[4:5], s[4:5], exec
	ds_read_b128 v[148:151], v13 offset:49152
	ds_read_b128 v[20:23], v15 offset:16384
	s_cselect_b32 s57, 0, s10
	s_cmp_lt_i32 s57, 2.0
	s_mul_i32 s4, s57, 0x60
	s_cselect_b32 s7, s47, 0
	s_cselect_b32 s10, s46, 0
	s_ashr_i32 s5, s4, 31
	ds_read_b128 v[152:155], v13 offset:51200
	s_waitcnt vmcnt(8)
	ds_read_b128 v[28:31], v15 offset:18432
	s_lshl_b64 s[4:5], s[4:5], 1
	ds_read_b128 v[160:163], v15 offset:20480
	v_add_u32_e32 v210, s6, v176
	s_add_u32 s4, s10, s4
	s_addc_u32 s5, s7, s5
	v_mov_b32_e32 v169, v12
	v_min_i32_e32 v2, 0x405f, v210
	v_lshl_add_u64 v[208:209], s[4:5], 0, v[168:169]
	v_min_i32_e32 v0, 0x407f, v210
	v_add_u32_e32 v2, 32, v2
	v_mad_i64_i32 v[0:1], s[6:7], v0, s83, v[208:209]
	v_mad_i64_i32 v[4:5], s[6:7], v2, s83, v[208:209]
	ds_read_b128 v[204:207], v15 offset:22528
	s_waitcnt lgkmcnt(1)
	v_mfma_f32_16x16x32_bf16 v[140:143], v[148:151], v[160:163], v[132:135]
	v_lshl_add_u32 v24, s9, 7, v174
	v_ashrrev_i32_e32 v25, 31, v24
	s_lshl_b32 s4, s57, 6
	ds_read_b128 v[132:135], v13 offset:53248
	global_load_dwordx4 v[0:3], v[0:1], off
	s_nop 0
	global_load_dwordx4 v[4:7], v[4:5], off
	ds_read_b128 v[156:159], v13 offset:55296
	v_lshlrev_b64 v[24:25], 11, v[24:25]
	s_ashr_i32 s5, s4, 31
	v_lshl_add_u64 v[24:25], s[50:51], 0, v[24:25]
	v_lshl_add_u64 v[24:25], s[4:5], 1, v[24:25]
	v_mov_b32_e32 v171, v12
	v_min_i32_e32 v8, 0x403f, v210
	v_min_i32_e32 v10, 0x401f, v210
	v_lshl_add_u64 v[24:25], v[24:25], 0, v[170:171]
	v_sub_u32_e32 v13, v210, v173
	v_add_u32_e32 v8, 64, v8
	v_add_u32_e32 v10, 0x60, v10
	v_add_co_u32_e32 v26, vcc, s2, v24
	v_add_u32_e32 v13, 0x80, v13
	v_mfma_f32_16x16x32_bf16 v[128:131], v[148:151], v[28:31], v[128:131]
	v_mad_i64_i32 v[8:9], s[6:7], v8, s83, v[208:209]
	v_mad_i64_i32 v[16:17], s[6:7], v10, s83, v[208:209]
	v_mfma_f32_16x16x32_bf16 v[116:119], v[152:155], v[28:31], v[116:119]
	v_addc_co_u32_e32 v27, vcc, 0, v25, vcc
	global_load_dwordx4 v[8:11], v[8:9], off
	s_nop 0
	global_load_dwordx4 v[16:19], v[16:17], off
	s_waitcnt lgkmcnt(1)
	v_mfma_f32_16x16x32_bf16 v[96:99], v[132:135], v[28:31], v[96:99]
	s_waitcnt lgkmcnt(0)
	v_mfma_f32_16x16x32_bf16 v[76:79], v[156:159], v[28:31], v[76:79]
	v_mad_i64_i32 v[28:29], s[4:5], v13, s83, v[208:209]
	v_mfma_f32_16x16x32_bf16 v[136:139], v[148:151], v[20:23], v[136:139]
	v_mfma_f32_16x16x32_bf16 v[120:123], v[152:155], v[20:23], v[120:123]
	v_mfma_f32_16x16x32_bf16 v[144:147], v[132:135], v[20:23], v[104:107]
	v_mfma_f32_16x16x32_bf16 v[80:83], v[156:159], v[20:23], v[80:83]
	global_load_dwordx4 v[20:23], v[24:25], off
	s_nop 0
	global_load_dwordx4 v[24:27], v[26:27], off
	ds_read_b128 v[104:107], v185 offset:128
	global_load_dwordx4 v[28:31], v[28:29], off
	s_sub_u32 s101, s8, 0
	s_lshr_b32 s101, s101, 1
	s_lshl_b32 s101, s101, 14
	s_add_u32 s101, s101, s100
	v_add_u32_e32 v250, s101, v251
	s_sub_u32 s101, s8, 0
	s_cmp_le_u32 s101, 14
	s_cselect_b32 s101, -1, 0
	v_and_b32_e32 v250, s101, v250
	global_load_dword v249, v250, s[52:53]
	v_mfma_f32_16x16x32_bf16 v[124:127], v[148:151], v[204:207], v[124:127]
	v_mfma_f32_16x16x32_bf16 v[112:115], v[152:155], v[160:163], v[112:115]
	v_mfma_f32_16x16x32_bf16 v[100:103], v[152:155], v[204:207], v[100:103]
	v_mfma_f32_16x16x32_bf16 v[92:95], v[132:135], v[160:163], v[92:95]
	v_mfma_f32_16x16x32_bf16 v[84:87], v[132:135], v[204:207], v[84:87]
	v_mfma_f32_16x16x32_bf16 v[72:75], v[156:159], v[160:163], v[72:75]
	v_mfma_f32_16x16x32_bf16 v[68:71], v[156:159], v[204:207], v[68:71]
	s_and_saveexec_b64 s[4:5], s[40:41]
	s_xor_b64 s[4:5], exec, s[4:5]
	s_cbranch_execz .LBB0_959
	s_waitcnt lgkmcnt(0)
	v_mfma_f32_16x16x32_bf16 v[36:39], v[132:135], v[104:107], v[36:39]
	v_mfma_f32_16x16x32_bf16 v[32:35], v[156:159], v[104:107], v[32:35]

; __device__ __forceinline__ float bflo(unsigned v) { return __uint_as_float(v << 16); }
; __device__ __forceinline__ float bfhi(unsigned v) { return __uint_as_float(v & 0xffff0000u); }
; template <int EPI, int TI>
; __device__ __forceinline__ void gemm_epilogue(const WS& ws, const f32x4 (&acc)[4][TI], const float (&rs)[TI], int tok0, int n0,
;                                               int wm, int wn, int lr, int lq, bool dry) {
;     ...
;   } else {
; #pragma unroll
;     for (int ni = 0; ni < 4; ++ni)
; #pragma unroll
;       for (int ti = 0; ti < TI; ++ti) {
;         if (!(ti < 4 || (lr == 0 && (ni >> 1) == wn))) continue;
;         const size_t off = (size_t)(ti < 4 ? tokr(ti) : tok0 + 128) * 1024 + nw + ni * 16 + 4 * lq;
;         const u32x2 hi = *(const u32x2*)(ws.HHI + off), lo = *(const u32x2*)(ws.HLO + off);
;         const float h0 = bflo(hi.x) + bflo(lo.x) + acc[ni][ti][0], h1 = bfhi(hi.x) + bfhi(lo.x) + acc[ni][ti][1];
;         const float h2 = bflo(hi.y) + bflo(lo.y) + acc[ni][ti][2], h3 = bfhi(hi.y) + bfhi(lo.y) + acc[ni][ti][3];
;         u32x2 nh; nh.x = cvt_pk_bf16(h0, h1); nh.y = cvt_pk_bf16(h2, h3);
;         u32x2 nl; nl.x = cvt_pk_bf16(h0 - bflo(nh.x), h1 - bfhi(nh.x)); nl.y = cvt_pk_bf16(h2 - bflo(nh.y), h3 - bfhi(nh.y));
;         if (!dry) { *(u32x2*)(ws.HHI + off) = nh; *(u32x2*)(ws.HLO + off) = nl; }
;       }
.LBB0_971:
	s_waitcnt lgkmcnt(0)
	v_mbcnt_lo_u32_b32 v13, -1, 0
	v_mbcnt_hi_u32_b32 v13, -1, v13
	s_add_i32 s5, s4, 0x80
	v_and_b32_e32 v14, 3, v13
	v_lshrrev_b32_e32 v13, 2, v13
	s_lshl_b32 s5, s5, 11
	v_lshl_add_u32 v15, v14, 4, v13
	v_and_b32_e32 v247, 64, v184
	v_lshlrev_b32_e32 v15, 2, v15
	v_add3_u32 v13, s4, v247, v13
	v_lshl_add_u32 v247, s6, 7, v183
	s_mov_b64 s[6:7], exec
	v_lshl_add_u32 v14, v14, 2, v247
	v_or_b32_e32 v247, v247, v172
	v_lshlrev_b32_e32 v14, 1, v14
	v_lshlrev_b32_e32 v247, 1, v247
	v_lshl_add_u32 v242, v13, 11, v14
	v_add_u32_e32 v246, s5, v247
	v_add_u32_e32 v243, 0x8000, v242
	v_add_u32_e32 v244, 0x10000, v242
	v_add_u32_e32 v245, 0x18000, v242
	s_and_b64 exec, s[6:7], s[42:43]
	global_load_dwordx2 v[204:205], v246, s[44:45]
	global_load_dwordx2 v[206:207], v246, s[52:53]
	global_load_dwordx2 v[208:209], v246, s[44:45] offset:32
	global_load_dwordx2 v[210:211], v246, s[52:53] offset:32
	s_and_b64 exec, s[6:7], s[54:55]
	global_load_dwordx2 v[212:213], v246, s[44:45] offset:64
	global_load_dwordx2 v[214:215], v246, s[52:53] offset:64
	global_load_dwordx2 v[216:217], v246, s[44:45] offset:96
	global_load_dwordx2 v[218:219], v246, s[52:53] offset:96
	s_mov_b64 exec, s[6:7]
	global_load_dwordx2 v[140:141], v242, s[44:45]
	global_load_dwordx2 v[142:143], v242, s[52:53]
	global_load_dwordx2 v[144:145], v242, s[44:45] offset:32
	global_load_dwordx2 v[146:147], v242, s[52:53] offset:32
	global_load_dwordx2 v[148:149], v242, s[44:45] offset:64
	global_load_dwordx2 v[150:151], v242, s[52:53] offset:64
	global_load_dwordx2 v[152:153], v242, s[44:45] offset:96
	global_load_dwordx2 v[154:155], v242, s[52:53] offset:96
	global_load_dwordx2 v[156:157], v243, s[44:45]
	global_load_dwordx2 v[158:159], v243, s[52:53]
	ds_bpermute_b32 v136, v15, v136
	ds_bpermute_b32 v137, v15, v137
	ds_bpermute_b32 v138, v15, v138
	ds_bpermute_b32 v139, v15, v139
	ds_bpermute_b32 v120, v15, v120
	ds_bpermute_b32 v121, v15, v121
	ds_bpermute_b32 v122, v15, v122
	ds_bpermute_b32 v123, v15, v123
	ds_bpermute_b32 v100, v15, v100
	ds_bpermute_b32 v101, v15, v101
	ds_bpermute_b32 v102, v15, v102
	ds_bpermute_b32 v103, v15, v103
	s_waitcnt vmcnt(8)
	s_waitcnt lgkmcnt(8)
	v_lshlrev_b32_e32 v252, 16, v140
	v_and_b32_e32 v253, 0xffff0000, v140
	v_lshlrev_b32_e32 v160, 16, v142
	v_and_b32_e32 v161, 0xffff0000, v142
	v_lshlrev_b32_e32 v254, 16, v141
	v_and_b32_e32 v255, 0xffff0000, v141
	v_lshlrev_b32_e32 v162, 16, v143
	v_and_b32_e32 v163, 0xffff0000, v143
	v_pk_add_f32 v[252:253], v[252:253], v[160:161]
	v_pk_add_f32 v[254:255], v[254:255], v[162:163]
	v_pk_add_f32 v[136:137], v[136:137], v[252:253]
	v_pk_add_f32 v[138:139], v[138:139], v[254:255]
	v_cvt_pk_bf16_f32 v140, v136, v137
	v_cvt_pk_bf16_f32 v141, v138, v139
	v_lshlrev_b32_e32 v252, 16, v140
	v_and_b32_e32 v253, 0xffff0000, v140
	v_lshlrev_b32_e32 v254, 16, v141
	v_and_b32_e32 v255, 0xffff0000, v141
	v_pk_add_f32 v[136:137], v[136:137], v[252:253] neg_lo:[0,1] neg_hi:[0,1]
	v_pk_add_f32 v[138:139], v[138:139], v[254:255] neg_lo:[0,1] neg_hi:[0,1]
	v_cvt_pk_bf16_f32 v142, v136, v137
	v_cvt_pk_bf16_f32 v143, v138, v139
	global_store_dwordx2 v242, v[140:141], s[44:45]
	global_store_dwordx2 v242, v[142:143], s[52:53]
	global_load_dwordx2 v[140:141], v243, s[44:45] offset:32
	global_load_dwordx2 v[142:143], v243, s[52:53] offset:32
	ds_bpermute_b32 v80, v15, v80
	ds_bpermute_b32 v81, v15, v81
	ds_bpermute_b32 v82, v15, v82
	ds_bpermute_b32 v83, v15, v83
	s_waitcnt vmcnt(10)
	s_waitcnt lgkmcnt(8)
	v_lshlrev_b32_e32 v252, 16, v144
	v_and_b32_e32 v253, 0xffff0000, v144
	v_lshlrev_b32_e32 v160, 16, v146
	v_and_b32_e32 v161, 0xffff0000, v146
	v_lshlrev_b32_e32 v254, 16, v145
	v_and_b32_e32 v255, 0xffff0000, v145
	v_lshlrev_b32_e32 v162, 16, v147
	v_and_b32_e32 v163, 0xffff0000, v147
	v_pk_add_f32 v[252:253], v[252:253], v[160:161]
	v_pk_add_f32 v[254:255], v[254:255], v[162:163]
	v_pk_add_f32 v[120:121], v[120:121], v[252:253]
	v_pk_add_f32 v[122:123], v[122:123], v[254:255]
	v_cvt_pk_bf16_f32 v144, v120, v121
	v_cvt_pk_bf16_f32 v145, v122, v123
	v_lshlrev_b32_e32 v252, 16, v144
	v_and_b32_e32 v253, 0xffff0000, v144
	v_lshlrev_b32_e32 v254, 16, v145
	v_and_b32_e32 v255, 0xffff0000, v145
	v_pk_add_f32 v[120:121], v[120:121], v[252:253] neg_lo:[0,1] neg_hi:[0,1]
	v_pk_add_f32 v[122:123], v[122:123], v[254:255] neg_lo:[0,1] neg_hi:[0,1]
	v_cvt_pk_bf16_f32 v146, v120, v121
	v_cvt_pk_bf16_f32 v147, v122, v123
	global_store_dwordx2 v242, v[144:145], s[44:45] offset:32
	global_store_dwordx2 v242, v[146:147], s[52:53] offset:32
	global_load_dwordx2 v[144:145], v243, s[44:45] offset:64
	global_load_dwordx2 v[146:147], v243, s[52:53] offset:64
	ds_bpermute_b32 v132, v15, v132
	ds_bpermute_b32 v133, v15, v133
	ds_bpermute_b32 v134, v15, v134
	ds_bpermute_b32 v135, v15, v135
	s_waitcnt vmcnt(12)
	s_waitcnt lgkmcnt(8)
	v_lshlrev_b32_e32 v252, 16, v148
	v_and_b32_e32 v253, 0xffff0000, v148
	v_lshlrev_b32_e32 v160, 16, v150
	v_and_b32_e32 v161, 0xffff0000, v150
	v_lshlrev_b32_e32 v254, 16, v149
	v_and_b32_e32 v255, 0xffff0000, v149
	v_lshlrev_b32_e32 v162, 16, v151
	v_and_b32_e32 v163, 0xffff0000, v151
	v_pk_add_f32 v[252:253], v[252:253], v[160:161]
	v_pk_add_f32 v[254:255], v[254:255], v[162:163]
	v_pk_add_f32 v[100:101], v[100:101], v[252:253]
	v_pk_add_f32 v[102:103], v[102:103], v[254:255]
	v_cvt_pk_bf16_f32 v148, v100, v101
	v_cvt_pk_bf16_f32 v149, v102, v103
	v_lshlrev_b32_e32 v252, 16, v148
	v_and_b32_e32 v253, 0xffff0000, v148
	v_lshlrev_b32_e32 v254, 16, v149
	v_and_b32_e32 v255, 0xffff0000, v149
	v_pk_add_f32 v[100:101], v[100:101], v[252:253] neg_lo:[0,1] neg_hi:[0,1]
	v_pk_add_f32 v[102:103], v[102:103], v[254:255] neg_lo:[0,1] neg_hi:[0,1]
	v_cvt_pk_bf16_f32 v150, v100, v101
	v_cvt_pk_bf16_f32 v151, v102, v103
	global_store_dwordx2 v242, v[148:149], s[44:45] offset:64
	global_store_dwordx2 v242, v[150:151], s[52:53] offset:64
	global_load_dwordx2 v[148:149], v243, s[44:45] offset:96
	global_load_dwordx2 v[150:151], v243, s[52:53] offset:96
	ds_bpermute_b32 v116, v15, v116
	ds_bpermute_b32 v117, v15, v117
	ds_bpermute_b32 v118, v15, v118
	ds_bpermute_b32 v119, v15, v119
	s_waitcnt vmcnt(14)
; __device__ __forceinline__ float bflo(unsigned v) { return __uint_as_float(v << 16); }
; __device__ __forceinline__ float bfhi(unsigned v) { return __uint_as_float(v & 0xffff0000u); }
; template <int EPI, int TI>
; __device__ __forceinline__ void gemm_epilogue(const WS& ws, const f32x4 (&acc)[4][TI], const float (&rs)[TI], int tok0, int n0,
;                                               int wm, int wn, int lr, int lq, bool dry) {
;     ...
;   } else {
; #pragma unroll
;     for (int ni = 0; ni < 4; ++ni)
; #pragma unroll
;       for (int ti = 0; ti < TI; ++ti) {
;         if (!(ti < 4 || (lr == 0 && (ni >> 1) == wn))) continue;
;         const size_t off = (size_t)(ti < 4 ? tokr(ti) : tok0 + 128) * 1024 + nw + ni * 16 + 4 * lq;
;         const u32x2 hi = *(const u32x2*)(ws.HHI + off), lo = *(const u32x2*)(ws.HLO + off);
;         const float h0 = bflo(hi.x) + bflo(lo.x) + acc[ni][ti][0], h1 = bfhi(hi.x) + bfhi(lo.x) + acc[ni][ti][1];
;         const float h2 = bflo(hi.y) + bflo(lo.y) + acc[ni][ti][2], h3 = bfhi(hi.y) + bfhi(lo.y) + acc[ni][ti][3];
;         u32x2 nh; nh.x = cvt_pk_bf16(h0, h1); nh.y = cvt_pk_bf16(h2, h3);
;         u32x2 nl; nl.x = cvt_pk_bf16(h0 - bflo(nh.x), h1 - bfhi(nh.x)); nl.y = cvt_pk_bf16(h2 - bflo(nh.y), h3 - bfhi(nh.y));
;         if (!dry) { *(u32x2*)(ws.HHI + off) = nh; *(u32x2*)(ws.HLO + off) = nl; }
;       }
	s_waitcnt lgkmcnt(8)
	v_lshlrev_b32_e32 v252, 16, v152
	v_and_b32_e32 v253, 0xffff0000, v152
	v_lshlrev_b32_e32 v160, 16, v154
	v_and_b32_e32 v161, 0xffff0000, v154
	v_lshlrev_b32_e32 v254, 16, v153
	v_and_b32_e32 v255, 0xffff0000, v153
	v_lshlrev_b32_e32 v162, 16, v155
	v_and_b32_e32 v163, 0xffff0000, v155
	v_pk_add_f32 v[252:253], v[252:253], v[160:161]
	v_pk_add_f32 v[254:255], v[254:255], v[162:163]
	v_pk_add_f32 v[80:81], v[80:81], v[252:253]
	v_pk_add_f32 v[82:83], v[82:83], v[254:255]
	v_cvt_pk_bf16_f32 v152, v80, v81
	v_cvt_pk_bf16_f32 v153, v82, v83
	v_lshlrev_b32_e32 v252, 16, v152
	v_and_b32_e32 v253, 0xffff0000, v152
	v_lshlrev_b32_e32 v254, 16, v153
	v_and_b32_e32 v255, 0xffff0000, v153
	v_pk_add_f32 v[80:81], v[80:81], v[252:253] neg_lo:[0,1] neg_hi:[0,1]
	v_pk_add_f32 v[82:83], v[82:83], v[254:255] neg_lo:[0,1] neg_hi:[0,1]
	v_cvt_pk_bf16_f32 v154, v80, v81
	v_cvt_pk_bf16_f32 v155, v82, v83
	global_store_dwordx2 v242, v[152:153], s[44:45] offset:96
	global_store_dwordx2 v242, v[154:155], s[52:53] offset:96
	global_load_dwordx2 v[152:153], v244, s[44:45]
	global_load_dwordx2 v[154:155], v244, s[52:53]
	ds_bpermute_b32 v96, v15, v96
	ds_bpermute_b32 v97, v15, v97
	ds_bpermute_b32 v98, v15, v98
	ds_bpermute_b32 v99, v15, v99
	s_waitcnt vmcnt(16)
	s_waitcnt lgkmcnt(8)
	v_lshlrev_b32_e32 v252, 16, v156
	v_and_b32_e32 v253, 0xffff0000, v156
	v_lshlrev_b32_e32 v160, 16, v158
	v_and_b32_e32 v161, 0xffff0000, v158
	v_lshlrev_b32_e32 v254, 16, v157
	v_and_b32_e32 v255, 0xffff0000, v157
	v_lshlrev_b32_e32 v162, 16, v159
	v_and_b32_e32 v163, 0xffff0000, v159
	v_pk_add_f32 v[252:253], v[252:253], v[160:161]
	v_pk_add_f32 v[254:255], v[254:255], v[162:163]
	v_pk_add_f32 v[132:133], v[132:133], v[252:253]
	v_pk_add_f32 v[134:135], v[134:135], v[254:255]
	v_cvt_pk_bf16_f32 v156, v132, v133
	v_cvt_pk_bf16_f32 v157, v134, v135
	v_lshlrev_b32_e32 v252, 16, v156
	v_and_b32_e32 v253, 0xffff0000, v156
	v_lshlrev_b32_e32 v254, 16, v157
	v_and_b32_e32 v255, 0xffff0000, v157
	v_pk_add_f32 v[132:133], v[132:133], v[252:253] neg_lo:[0,1] neg_hi:[0,1]
	v_pk_add_f32 v[134:135], v[134:135], v[254:255] neg_lo:[0,1] neg_hi:[0,1]
	v_cvt_pk_bf16_f32 v158, v132, v133
	v_cvt_pk_bf16_f32 v159, v134, v135
	global_store_dwordx2 v243, v[156:157], s[44:45]
	global_store_dwordx2 v243, v[158:159], s[52:53]
	global_load_dwordx2 v[156:157], v244, s[44:45] offset:32
	global_load_dwordx2 v[158:159], v244, s[52:53] offset:32
	ds_bpermute_b32 v76, v15, v76
	ds_bpermute_b32 v77, v15, v77
	ds_bpermute_b32 v78, v15, v78
	ds_bpermute_b32 v79, v15, v79
	s_waitcnt vmcnt(16)
	s_waitcnt lgkmcnt(8)
	v_lshlrev_b32_e32 v252, 16, v140
	v_and_b32_e32 v253, 0xffff0000, v140
	v_lshlrev_b32_e32 v160, 16, v142
	v_and_b32_e32 v161, 0xffff0000, v142
	v_lshlrev_b32_e32 v254, 16, v141
	v_and_b32_e32 v255, 0xffff0000, v141
	v_lshlrev_b32_e32 v162, 16, v143
	v_and_b32_e32 v163, 0xffff0000, v143
	v_pk_add_f32 v[252:253], v[252:253], v[160:161]
	v_pk_add_f32 v[254:255], v[254:255], v[162:163]
	v_pk_add_f32 v[116:117], v[116:117], v[252:253]
	v_pk_add_f32 v[118:119], v[118:119], v[254:255]
	v_cvt_pk_bf16_f32 v140, v116, v117
	v_cvt_pk_bf16_f32 v141, v118, v119
	v_lshlrev_b32_e32 v252, 16, v140
	v_and_b32_e32 v253, 0xffff0000, v140
	v_lshlrev_b32_e32 v254, 16, v141
	v_and_b32_e32 v255, 0xffff0000, v141
	v_pk_add_f32 v[116:117], v[116:117], v[252:253] neg_lo:[0,1] neg_hi:[0,1]
	v_pk_add_f32 v[118:119], v[118:119], v[254:255] neg_lo:[0,1] neg_hi:[0,1]
	v_cvt_pk_bf16_f32 v142, v116, v117
	v_cvt_pk_bf16_f32 v143, v118, v119
	global_store_dwordx2 v243, v[140:141], s[44:45] offset:32
	global_store_dwordx2 v243, v[142:143], s[52:53] offset:32
	global_load_dwordx2 v[140:141], v244, s[44:45] offset:64
	global_load_dwordx2 v[142:143], v244, s[52:53] offset:64
	ds_bpermute_b32 v128, v15, v128
	ds_bpermute_b32 v129, v15, v129
	ds_bpermute_b32 v130, v15, v130
	ds_bpermute_b32 v131, v15, v131
	s_waitcnt vmcnt(16)
	s_waitcnt lgkmcnt(8)
	v_lshlrev_b32_e32 v252, 16, v144
	v_and_b32_e32 v253, 0xffff0000, v144
	v_lshlrev_b32_e32 v160, 16, v146
	v_and_b32_e32 v161, 0xffff0000, v146
	v_lshlrev_b32_e32 v254, 16, v145
	v_and_b32_e32 v255, 0xffff0000, v145
	v_lshlrev_b32_e32 v162, 16, v147
	v_and_b32_e32 v163, 0xffff0000, v147
	v_pk_add_f32 v[252:253], v[252:253], v[160:161]
	v_pk_add_f32 v[254:255], v[254:255], v[162:163]
	v_pk_add_f32 v[96:97], v[96:97], v[252:253]
	v_pk_add_f32 v[98:99], v[98:99], v[254:255]
	v_cvt_pk_bf16_f32 v144, v96, v97
	v_cvt_pk_bf16_f32 v145, v98, v99
	v_lshlrev_b32_e32 v252, 16, v144
	v_and_b32_e32 v253, 0xffff0000, v144
	v_lshlrev_b32_e32 v254, 16, v145
	v_and_b32_e32 v255, 0xffff0000, v145
	v_pk_add_f32 v[96:97], v[96:97], v[252:253] neg_lo:[0,1] neg_hi:[0,1]
	v_pk_add_f32 v[98:99], v[98:99], v[254:255] neg_lo:[0,1] neg_hi:[0,1]
	v_cvt_pk_bf16_f32 v146, v96, v97
	v_cvt_pk_bf16_f32 v147, v98, v99
	global_store_dwordx2 v243, v[144:145], s[44:45] offset:64
	global_store_dwordx2 v243, v[146:147], s[52:53] offset:64
	global_load_dwordx2 v[144:145], v244, s[44:45] offset:96
	global_load_dwordx2 v[146:147], v244, s[52:53] offset:96
	ds_bpermute_b32 v112, v15, v112
	ds_bpermute_b32 v113, v15, v113
	ds_bpermute_b32 v114, v15, v114
	ds_bpermute_b32 v115, v15, v115
	s_waitcnt vmcnt(16)
	s_waitcnt lgkmcnt(8)
; __device__ __forceinline__ float bflo(unsigned v) { return __uint_as_float(v << 16); }
; __device__ __forceinline__ float bfhi(unsigned v) { return __uint_as_float(v & 0xffff0000u); }
; template <int EPI, int TI>
; __device__ __forceinline__ void gemm_epilogue(const WS& ws, const f32x4 (&acc)[4][TI], const float (&rs)[TI], int tok0, int n0,
;                                               int wm, int wn, int lr, int lq, bool dry) {
;     ...
;   } else {
; #pragma unroll
;     for (int ni = 0; ni < 4; ++ni)
; #pragma unroll
;       for (int ti = 0; ti < TI; ++ti) {
;         if (!(ti < 4 || (lr == 0 && (ni >> 1) == wn))) continue;
;         const size_t off = (size_t)(ti < 4 ? tokr(ti) : tok0 + 128) * 1024 + nw + ni * 16 + 4 * lq;
;         const u32x2 hi = *(const u32x2*)(ws.HHI + off), lo = *(const u32x2*)(ws.HLO + off);
;         const float h0 = bflo(hi.x) + bflo(lo.x) + acc[ni][ti][0], h1 = bfhi(hi.x) + bfhi(lo.x) + acc[ni][ti][1];
;         const float h2 = bflo(hi.y) + bflo(lo.y) + acc[ni][ti][2], h3 = bfhi(hi.y) + bfhi(lo.y) + acc[ni][ti][3];
;         u32x2 nh; nh.x = cvt_pk_bf16(h0, h1); nh.y = cvt_pk_bf16(h2, h3);
;         u32x2 nl; nl.x = cvt_pk_bf16(h0 - bflo(nh.x), h1 - bfhi(nh.x)); nl.y = cvt_pk_bf16(h2 - bflo(nh.y), h3 - bfhi(nh.y));
;         if (!dry) { *(u32x2*)(ws.HHI + off) = nh; *(u32x2*)(ws.HLO + off) = nl; }
;       }
	v_lshlrev_b32_e32 v252, 16, v148
	v_and_b32_e32 v253, 0xffff0000, v148
	v_lshlrev_b32_e32 v160, 16, v150
	v_and_b32_e32 v161, 0xffff0000, v150
	v_lshlrev_b32_e32 v254, 16, v149
	v_and_b32_e32 v255, 0xffff0000, v149
	v_lshlrev_b32_e32 v162, 16, v151
	v_and_b32_e32 v163, 0xffff0000, v151
	v_pk_add_f32 v[252:253], v[252:253], v[160:161]
	v_pk_add_f32 v[254:255], v[254:255], v[162:163]
	v_pk_add_f32 v[76:77], v[76:77], v[252:253]
	v_pk_add_f32 v[78:79], v[78:79], v[254:255]
	v_cvt_pk_bf16_f32 v148, v76, v77
	v_cvt_pk_bf16_f32 v149, v78, v79
	v_lshlrev_b32_e32 v252, 16, v148
	v_and_b32_e32 v253, 0xffff0000, v148
	v_lshlrev_b32_e32 v254, 16, v149
	v_and_b32_e32 v255, 0xffff0000, v149
	v_pk_add_f32 v[76:77], v[76:77], v[252:253] neg_lo:[0,1] neg_hi:[0,1]
	v_pk_add_f32 v[78:79], v[78:79], v[254:255] neg_lo:[0,1] neg_hi:[0,1]
	v_cvt_pk_bf16_f32 v150, v76, v77
	v_cvt_pk_bf16_f32 v151, v78, v79
	global_store_dwordx2 v243, v[148:149], s[44:45] offset:96
	global_store_dwordx2 v243, v[150:151], s[52:53] offset:96
	global_load_dwordx2 v[148:149], v245, s[44:45]
	global_load_dwordx2 v[150:151], v245, s[52:53]
	ds_bpermute_b32 v92, v15, v92
	ds_bpermute_b32 v93, v15, v93
	ds_bpermute_b32 v94, v15, v94
	ds_bpermute_b32 v95, v15, v95
	s_waitcnt vmcnt(16)
	s_waitcnt lgkmcnt(8)
	v_lshlrev_b32_e32 v252, 16, v152
	v_and_b32_e32 v253, 0xffff0000, v152
	v_lshlrev_b32_e32 v160, 16, v154
	v_and_b32_e32 v161, 0xffff0000, v154
	v_lshlrev_b32_e32 v254, 16, v153
	v_and_b32_e32 v255, 0xffff0000, v153
	v_lshlrev_b32_e32 v162, 16, v155
	v_and_b32_e32 v163, 0xffff0000, v155
	v_pk_add_f32 v[252:253], v[252:253], v[160:161]
	v_pk_add_f32 v[254:255], v[254:255], v[162:163]
	v_pk_add_f32 v[128:129], v[128:129], v[252:253]
	v_pk_add_f32 v[130:131], v[130:131], v[254:255]
	v_cvt_pk_bf16_f32 v152, v128, v129
	v_cvt_pk_bf16_f32 v153, v130, v131
	v_lshlrev_b32_e32 v252, 16, v152
	v_and_b32_e32 v253, 0xffff0000, v152
	v_lshlrev_b32_e32 v254, 16, v153
	v_and_b32_e32 v255, 0xffff0000, v153
	v_pk_add_f32 v[128:129], v[128:129], v[252:253] neg_lo:[0,1] neg_hi:[0,1]
	v_pk_add_f32 v[130:131], v[130:131], v[254:255] neg_lo:[0,1] neg_hi:[0,1]
	v_cvt_pk_bf16_f32 v154, v128, v129
	v_cvt_pk_bf16_f32 v155, v130, v131
	global_store_dwordx2 v244, v[152:153], s[44:45]
	global_store_dwordx2 v244, v[154:155], s[52:53]
	global_load_dwordx2 v[152:153], v245, s[44:45] offset:32
	global_load_dwordx2 v[154:155], v245, s[52:53] offset:32
	ds_bpermute_b32 v72, v15, v72
	ds_bpermute_b32 v73, v15, v73
	ds_bpermute_b32 v74, v15, v74
	ds_bpermute_b32 v75, v15, v75
	s_waitcnt vmcnt(16)
	s_waitcnt lgkmcnt(8)
	v_lshlrev_b32_e32 v252, 16, v156
	v_and_b32_e32 v253, 0xffff0000, v156
	v_lshlrev_b32_e32 v160, 16, v158
	v_and_b32_e32 v161, 0xffff0000, v158
	v_lshlrev_b32_e32 v254, 16, v157
	v_and_b32_e32 v255, 0xffff0000, v157
	v_lshlrev_b32_e32 v162, 16, v159
	v_and_b32_e32 v163, 0xffff0000, v159
	v_pk_add_f32 v[252:253], v[252:253], v[160:161]
	v_pk_add_f32 v[254:255], v[254:255], v[162:163]
	v_pk_add_f32 v[112:113], v[112:113], v[252:253]
	v_pk_add_f32 v[114:115], v[114:115], v[254:255]
	v_cvt_pk_bf16_f32 v156, v112, v113
	v_cvt_pk_bf16_f32 v157, v114, v115
	v_lshlrev_b32_e32 v252, 16, v156
	v_and_b32_e32 v253, 0xffff0000, v156
	v_lshlrev_b32_e32 v254, 16, v157
	v_and_b32_e32 v255, 0xffff0000, v157
	v_pk_add_f32 v[112:113], v[112:113], v[252:253] neg_lo:[0,1] neg_hi:[0,1]
	v_pk_add_f32 v[114:115], v[114:115], v[254:255] neg_lo:[0,1] neg_hi:[0,1]
	v_cvt_pk_bf16_f32 v158, v112, v113
	v_cvt_pk_bf16_f32 v159, v114, v115
	global_store_dwordx2 v244, v[156:157], s[44:45] offset:32
	global_store_dwordx2 v244, v[158:159], s[52:53] offset:32
	global_load_dwordx2 v[156:157], v245, s[44:45] offset:64
	global_load_dwordx2 v[158:159], v245, s[52:53] offset:64
	ds_bpermute_b32 v124, v15, v124
	ds_bpermute_b32 v125, v15, v125
	ds_bpermute_b32 v126, v15, v126
	ds_bpermute_b32 v127, v15, v127
	s_waitcnt vmcnt(16)
	s_waitcnt lgkmcnt(8)
	v_lshlrev_b32_e32 v252, 16, v140
	v_and_b32_e32 v253, 0xffff0000, v140
	v_lshlrev_b32_e32 v160, 16, v142
	v_and_b32_e32 v161, 0xffff0000, v142
	v_lshlrev_b32_e32 v254, 16, v141
	v_and_b32_e32 v255, 0xffff0000, v141
	v_lshlrev_b32_e32 v162, 16, v143
	v_and_b32_e32 v163, 0xffff0000, v143
	v_pk_add_f32 v[252:253], v[252:253], v[160:161]
	v_pk_add_f32 v[254:255], v[254:255], v[162:163]
	v_pk_add_f32 v[92:93], v[92:93], v[252:253]
	v_pk_add_f32 v[94:95], v[94:95], v[254:255]
	v_cvt_pk_bf16_f32 v140, v92, v93
	v_cvt_pk_bf16_f32 v141, v94, v95
	v_lshlrev_b32_e32 v252, 16, v140
	v_and_b32_e32 v253, 0xffff0000, v140
	v_lshlrev_b32_e32 v254, 16, v141
	v_and_b32_e32 v255, 0xffff0000, v141
	v_pk_add_f32 v[92:93], v[92:93], v[252:253] neg_lo:[0,1] neg_hi:[0,1]
	v_pk_add_f32 v[94:95], v[94:95], v[254:255] neg_lo:[0,1] neg_hi:[0,1]
	v_cvt_pk_bf16_f32 v142, v92, v93
	v_cvt_pk_bf16_f32 v143, v94, v95
	global_store_dwordx2 v244, v[140:141], s[44:45] offset:64
	global_store_dwordx2 v244, v[142:143], s[52:53] offset:64
	global_load_dwordx2 v[140:141], v245, s[44:45] offset:96
	global_load_dwordx2 v[142:143], v245, s[52:53] offset:96
	ds_bpermute_b32 v104, v15, v104
	ds_bpermute_b32 v105, v15, v105
	ds_bpermute_b32 v106, v15, v106
	ds_bpermute_b32 v107, v15, v107
	s_waitcnt vmcnt(16)
	s_waitcnt lgkmcnt(8)
; __device__ __forceinline__ float bflo(unsigned v) { return __uint_as_float(v << 16); }
; __device__ __forceinline__ float bfhi(unsigned v) { return __uint_as_float(v & 0xffff0000u); }
; template <int EPI, int TI>
; __device__ __forceinline__ void gemm_epilogue(const WS& ws, const f32x4 (&acc)[4][TI], const float (&rs)[TI], int tok0, int n0,
;                                               int wm, int wn, int lr, int lq, bool dry) {
;     ...
;   } else {
; #pragma unroll
;     for (int ni = 0; ni < 4; ++ni)
; #pragma unroll
;       for (int ti = 0; ti < TI; ++ti) {
;         if (!(ti < 4 || (lr == 0 && (ni >> 1) == wn))) continue;
;         const size_t off = (size_t)(ti < 4 ? tokr(ti) : tok0 + 128) * 1024 + nw + ni * 16 + 4 * lq;
;         const u32x2 hi = *(const u32x2*)(ws.HHI + off), lo = *(const u32x2*)(ws.HLO + off);
;         const float h0 = bflo(hi.x) + bflo(lo.x) + acc[ni][ti][0], h1 = bfhi(hi.x) + bfhi(lo.x) + acc[ni][ti][1];
;         const float h2 = bflo(hi.y) + bflo(lo.y) + acc[ni][ti][2], h3 = bfhi(hi.y) + bfhi(lo.y) + acc[ni][ti][3];
;         u32x2 nh; nh.x = cvt_pk_bf16(h0, h1); nh.y = cvt_pk_bf16(h2, h3);
;         u32x2 nl; nl.x = cvt_pk_bf16(h0 - bflo(nh.x), h1 - bfhi(nh.x)); nl.y = cvt_pk_bf16(h2 - bflo(nh.y), h3 - bfhi(nh.y));
;         if (!dry) { *(u32x2*)(ws.HHI + off) = nh; *(u32x2*)(ws.HLO + off) = nl; }
;       }
	v_lshlrev_b32_e32 v252, 16, v144
	v_and_b32_e32 v253, 0xffff0000, v144
	v_lshlrev_b32_e32 v160, 16, v146
	v_and_b32_e32 v161, 0xffff0000, v146
	v_lshlrev_b32_e32 v254, 16, v145
	v_and_b32_e32 v255, 0xffff0000, v145
	v_lshlrev_b32_e32 v162, 16, v147
	v_and_b32_e32 v163, 0xffff0000, v147
	v_pk_add_f32 v[252:253], v[252:253], v[160:161]
	v_pk_add_f32 v[254:255], v[254:255], v[162:163]
	v_pk_add_f32 v[72:73], v[72:73], v[252:253]
	v_pk_add_f32 v[74:75], v[74:75], v[254:255]
	v_cvt_pk_bf16_f32 v144, v72, v73
	v_cvt_pk_bf16_f32 v145, v74, v75
	v_lshlrev_b32_e32 v252, 16, v144
	v_and_b32_e32 v253, 0xffff0000, v144
	v_lshlrev_b32_e32 v254, 16, v145
	v_and_b32_e32 v255, 0xffff0000, v145
	v_pk_add_f32 v[72:73], v[72:73], v[252:253] neg_lo:[0,1] neg_hi:[0,1]
	v_pk_add_f32 v[74:75], v[74:75], v[254:255] neg_lo:[0,1] neg_hi:[0,1]
	v_cvt_pk_bf16_f32 v146, v72, v73
	v_cvt_pk_bf16_f32 v147, v74, v75
	global_store_dwordx2 v244, v[144:145], s[44:45] offset:96
	global_store_dwordx2 v244, v[146:147], s[52:53] offset:96
	ds_bpermute_b32 v84, v15, v84
	ds_bpermute_b32 v85, v15, v85
	ds_bpermute_b32 v86, v15, v86
	ds_bpermute_b32 v87, v15, v87
	s_waitcnt vmcnt(14)
	s_waitcnt lgkmcnt(8)
	v_lshlrev_b32_e32 v252, 16, v148
	v_and_b32_e32 v253, 0xffff0000, v148
	v_lshlrev_b32_e32 v160, 16, v150
	v_and_b32_e32 v161, 0xffff0000, v150
	v_lshlrev_b32_e32 v254, 16, v149
	v_and_b32_e32 v255, 0xffff0000, v149
	v_lshlrev_b32_e32 v162, 16, v151
	v_and_b32_e32 v163, 0xffff0000, v151
	v_pk_add_f32 v[252:253], v[252:253], v[160:161]
	v_pk_add_f32 v[254:255], v[254:255], v[162:163]
	v_pk_add_f32 v[124:125], v[124:125], v[252:253]
	v_pk_add_f32 v[126:127], v[126:127], v[254:255]
	v_cvt_pk_bf16_f32 v148, v124, v125
	v_cvt_pk_bf16_f32 v149, v126, v127
	v_lshlrev_b32_e32 v252, 16, v148
	v_and_b32_e32 v253, 0xffff0000, v148
	v_lshlrev_b32_e32 v254, 16, v149
	v_and_b32_e32 v255, 0xffff0000, v149
	v_pk_add_f32 v[124:125], v[124:125], v[252:253] neg_lo:[0,1] neg_hi:[0,1]
	v_pk_add_f32 v[126:127], v[126:127], v[254:255] neg_lo:[0,1] neg_hi:[0,1]
	v_cvt_pk_bf16_f32 v150, v124, v125
	v_cvt_pk_bf16_f32 v151, v126, v127
	global_store_dwordx2 v245, v[148:149], s[44:45]
	global_store_dwordx2 v245, v[150:151], s[52:53]
	ds_bpermute_b32 v68, v15, v68
	ds_bpermute_b32 v69, v15, v69
	ds_bpermute_b32 v70, v15, v70
	ds_bpermute_b32 v71, v15, v71
	s_waitcnt vmcnt(12)
	s_waitcnt lgkmcnt(8)
	v_lshlrev_b32_e32 v252, 16, v152
	v_and_b32_e32 v253, 0xffff0000, v152
	v_lshlrev_b32_e32 v160, 16, v154
	v_and_b32_e32 v161, 0xffff0000, v154
	v_lshlrev_b32_e32 v254, 16, v153
	v_and_b32_e32 v255, 0xffff0000, v153
	v_lshlrev_b32_e32 v162, 16, v155
	v_and_b32_e32 v163, 0xffff0000, v155
	v_pk_add_f32 v[252:253], v[252:253], v[160:161]
	v_pk_add_f32 v[254:255], v[254:255], v[162:163]
	v_pk_add_f32 v[104:105], v[104:105], v[252:253]
	v_pk_add_f32 v[106:107], v[106:107], v[254:255]
	v_cvt_pk_bf16_f32 v152, v104, v105
	v_cvt_pk_bf16_f32 v153, v106, v107
	v_lshlrev_b32_e32 v252, 16, v152
	v_and_b32_e32 v253, 0xffff0000, v152
	v_lshlrev_b32_e32 v254, 16, v153
	v_and_b32_e32 v255, 0xffff0000, v153
	v_pk_add_f32 v[104:105], v[104:105], v[252:253] neg_lo:[0,1] neg_hi:[0,1]
	v_pk_add_f32 v[106:107], v[106:107], v[254:255] neg_lo:[0,1] neg_hi:[0,1]
	v_cvt_pk_bf16_f32 v154, v104, v105
	v_cvt_pk_bf16_f32 v155, v106, v107
	global_store_dwordx2 v245, v[152:153], s[44:45] offset:32
	global_store_dwordx2 v245, v[154:155], s[52:53] offset:32
	s_waitcnt vmcnt(10)
	s_waitcnt lgkmcnt(4)
	v_lshlrev_b32_e32 v252, 16, v156
	v_and_b32_e32 v253, 0xffff0000, v156
	v_lshlrev_b32_e32 v160, 16, v158
	v_and_b32_e32 v161, 0xffff0000, v158
	v_lshlrev_b32_e32 v254, 16, v157
	v_and_b32_e32 v255, 0xffff0000, v157
	v_lshlrev_b32_e32 v162, 16, v159
	v_and_b32_e32 v163, 0xffff0000, v159
	v_pk_add_f32 v[252:253], v[252:253], v[160:161]
	v_pk_add_f32 v[254:255], v[254:255], v[162:163]
	v_pk_add_f32 v[84:85], v[84:85], v[252:253]
	v_pk_add_f32 v[86:87], v[86:87], v[254:255]
	v_cvt_pk_bf16_f32 v156, v84, v85
	v_cvt_pk_bf16_f32 v157, v86, v87
	v_lshlrev_b32_e32 v252, 16, v156
	v_and_b32_e32 v253, 0xffff0000, v156
	v_lshlrev_b32_e32 v254, 16, v157
	v_and_b32_e32 v255, 0xffff0000, v157
	v_pk_add_f32 v[84:85], v[84:85], v[252:253] neg_lo:[0,1] neg_hi:[0,1]
	v_pk_add_f32 v[86:87], v[86:87], v[254:255] neg_lo:[0,1] neg_hi:[0,1]
	v_cvt_pk_bf16_f32 v158, v84, v85
	v_cvt_pk_bf16_f32 v159, v86, v87
	global_store_dwordx2 v245, v[156:157], s[44:45] offset:64
	global_store_dwordx2 v245, v[158:159], s[52:53] offset:64
	s_waitcnt vmcnt(8)
	s_waitcnt lgkmcnt(0)
; __device__ __forceinline__ float bflo(unsigned v) { return __uint_as_float(v << 16); }
; __device__ __forceinline__ float bfhi(unsigned v) { return __uint_as_float(v & 0xffff0000u); }
; template <int EPI, int TI>
; __device__ __forceinline__ void gemm_epilogue(const WS& ws, const f32x4 (&acc)[4][TI], const float (&rs)[TI], int tok0, int n0,
;                                               int wm, int wn, int lr, int lq, bool dry) {
;     ...
;   } else {
; #pragma unroll
;     for (int ni = 0; ni < 4; ++ni)
; #pragma unroll
;       for (int ti = 0; ti < TI; ++ti) {
;         if (!(ti < 4 || (lr == 0 && (ni >> 1) == wn))) continue;
;         const size_t off = (size_t)(ti < 4 ? tokr(ti) : tok0 + 128) * 1024 + nw + ni * 16 + 4 * lq;
;         const u32x2 hi = *(const u32x2*)(ws.HHI + off), lo = *(const u32x2*)(ws.HLO + off);
;         const float h0 = bflo(hi.x) + bflo(lo.x) + acc[ni][ti][0], h1 = bfhi(hi.x) + bfhi(lo.x) + acc[ni][ti][1];
;         const float h2 = bflo(hi.y) + bflo(lo.y) + acc[ni][ti][2], h3 = bfhi(hi.y) + bfhi(lo.y) + acc[ni][ti][3];
;         u32x2 nh; nh.x = cvt_pk_bf16(h0, h1); nh.y = cvt_pk_bf16(h2, h3);
;         u32x2 nl; nl.x = cvt_pk_bf16(h0 - bflo(nh.x), h1 - bfhi(nh.x)); nl.y = cvt_pk_bf16(h2 - bflo(nh.y), h3 - bfhi(nh.y));
;         if (!dry) { *(u32x2*)(ws.HHI + off) = nh; *(u32x2*)(ws.HLO + off) = nl; }
;       }
	v_lshlrev_b32_e32 v252, 16, v140
	v_and_b32_e32 v253, 0xffff0000, v140
	v_lshlrev_b32_e32 v160, 16, v142
	v_and_b32_e32 v161, 0xffff0000, v142
	v_lshlrev_b32_e32 v254, 16, v141
	v_and_b32_e32 v255, 0xffff0000, v141
	v_lshlrev_b32_e32 v162, 16, v143
	v_and_b32_e32 v163, 0xffff0000, v143
	v_pk_add_f32 v[252:253], v[252:253], v[160:161]
	v_pk_add_f32 v[254:255], v[254:255], v[162:163]
	v_pk_add_f32 v[68:69], v[68:69], v[252:253]
	v_pk_add_f32 v[70:71], v[70:71], v[254:255]
	v_cvt_pk_bf16_f32 v140, v68, v69
	v_cvt_pk_bf16_f32 v141, v70, v71
	v_lshlrev_b32_e32 v252, 16, v140
	v_and_b32_e32 v253, 0xffff0000, v140
	v_lshlrev_b32_e32 v254, 16, v141
	v_and_b32_e32 v255, 0xffff0000, v141
	v_pk_add_f32 v[68:69], v[68:69], v[252:253] neg_lo:[0,1] neg_hi:[0,1]
	v_pk_add_f32 v[70:71], v[70:71], v[254:255] neg_lo:[0,1] neg_hi:[0,1]
	v_cvt_pk_bf16_f32 v142, v68, v69
	v_cvt_pk_bf16_f32 v143, v70, v71
	global_store_dwordx2 v245, v[140:141], s[44:45] offset:96
	global_store_dwordx2 v245, v[142:143], s[52:53] offset:96
	s_and_b64 exec, s[6:7], s[42:43]
	s_waitcnt vmcnt(63)
	v_lshlrev_b32_e32 v252, 16, v204
	v_and_b32_e32 v253, 0xffff0000, v204
	v_lshlrev_b32_e32 v160, 16, v206
	v_and_b32_e32 v161, 0xffff0000, v206
	v_lshlrev_b32_e32 v254, 16, v205
	v_and_b32_e32 v255, 0xffff0000, v205
	v_lshlrev_b32_e32 v162, 16, v207
	v_and_b32_e32 v163, 0xffff0000, v207
	v_pk_add_f32 v[252:253], v[252:253], v[160:161]
	v_pk_add_f32 v[254:255], v[254:255], v[162:163]
	v_pk_add_f32 v[108:109], v[108:109], v[252:253]
	v_pk_add_f32 v[110:111], v[110:111], v[254:255]
	v_cvt_pk_bf16_f32 v204, v108, v109
	v_cvt_pk_bf16_f32 v205, v110, v111
	v_lshlrev_b32_e32 v252, 16, v204
	v_and_b32_e32 v253, 0xffff0000, v204
	v_lshlrev_b32_e32 v254, 16, v205
	v_and_b32_e32 v255, 0xffff0000, v205
	v_pk_add_f32 v[108:109], v[108:109], v[252:253] neg_lo:[0,1] neg_hi:[0,1]
	v_pk_add_f32 v[110:111], v[110:111], v[254:255] neg_lo:[0,1] neg_hi:[0,1]
	v_cvt_pk_bf16_f32 v206, v108, v109
	v_cvt_pk_bf16_f32 v207, v110, v111
	global_store_dwordx2 v246, v[204:205], s[44:45]
	global_store_dwordx2 v246, v[206:207], s[52:53]
	s_waitcnt vmcnt(63)
	v_lshlrev_b32_e32 v252, 16, v208
	v_and_b32_e32 v253, 0xffff0000, v208
	v_lshlrev_b32_e32 v160, 16, v210
	v_and_b32_e32 v161, 0xffff0000, v210
	v_lshlrev_b32_e32 v254, 16, v209
	v_and_b32_e32 v255, 0xffff0000, v209
	v_lshlrev_b32_e32 v162, 16, v211
	v_and_b32_e32 v163, 0xffff0000, v211
	v_pk_add_f32 v[252:253], v[252:253], v[160:161]
	v_pk_add_f32 v[254:255], v[254:255], v[162:163]
	v_pk_add_f32 v[88:89], v[88:89], v[252:253]
	v_pk_add_f32 v[90:91], v[90:91], v[254:255]
	v_cvt_pk_bf16_f32 v208, v88, v89
	v_cvt_pk_bf16_f32 v209, v90, v91
	v_lshlrev_b32_e32 v252, 16, v208
	v_and_b32_e32 v253, 0xffff0000, v208
	v_lshlrev_b32_e32 v254, 16, v209
	v_and_b32_e32 v255, 0xffff0000, v209
	v_pk_add_f32 v[88:89], v[88:89], v[252:253] neg_lo:[0,1] neg_hi:[0,1]
	v_pk_add_f32 v[90:91], v[90:91], v[254:255] neg_lo:[0,1] neg_hi:[0,1]
	v_cvt_pk_bf16_f32 v210, v88, v89
	v_cvt_pk_bf16_f32 v211, v90, v91
	global_store_dwordx2 v246, v[208:209], s[44:45] offset:32
	global_store_dwordx2 v246, v[210:211], s[52:53] offset:32
	s_and_b64 exec, s[6:7], s[54:55]
	s_waitcnt vmcnt(63)
	v_lshlrev_b32_e32 v252, 16, v212
	v_and_b32_e32 v253, 0xffff0000, v212
	v_lshlrev_b32_e32 v160, 16, v214
	v_and_b32_e32 v161, 0xffff0000, v214
	v_lshlrev_b32_e32 v254, 16, v213
	v_and_b32_e32 v255, 0xffff0000, v213
	v_lshlrev_b32_e32 v162, 16, v215
	v_and_b32_e32 v163, 0xffff0000, v215
	v_pk_add_f32 v[252:253], v[252:253], v[160:161]
	v_pk_add_f32 v[254:255], v[254:255], v[162:163]
	v_pk_add_f32 v[36:37], v[36:37], v[252:253]
	v_pk_add_f32 v[38:39], v[38:39], v[254:255]
	v_cvt_pk_bf16_f32 v212, v36, v37
	v_cvt_pk_bf16_f32 v213, v38, v39
	v_lshlrev_b32_e32 v252, 16, v212
	v_and_b32_e32 v253, 0xffff0000, v212
	v_lshlrev_b32_e32 v254, 16, v213
	v_and_b32_e32 v255, 0xffff0000, v213
	v_pk_add_f32 v[36:37], v[36:37], v[252:253] neg_lo:[0,1] neg_hi:[0,1]
	v_pk_add_f32 v[38:39], v[38:39], v[254:255] neg_lo:[0,1] neg_hi:[0,1]
	v_cvt_pk_bf16_f32 v214, v36, v37
	v_cvt_pk_bf16_f32 v215, v38, v39
	global_store_dwordx2 v246, v[212:213], s[44:45] offset:64
	global_store_dwordx2 v246, v[214:215], s[52:53] offset:64
	s_waitcnt vmcnt(63)
	v_lshlrev_b32_e32 v252, 16, v216
	v_and_b32_e32 v253, 0xffff0000, v216
	v_lshlrev_b32_e32 v160, 16, v218
	v_and_b32_e32 v161, 0xffff0000, v218
	v_lshlrev_b32_e32 v254, 16, v217
	v_and_b32_e32 v255, 0xffff0000, v217
	v_lshlrev_b32_e32 v162, 16, v219
	v_and_b32_e32 v163, 0xffff0000, v219
	v_pk_add_f32 v[252:253], v[252:253], v[160:161]
	v_pk_add_f32 v[254:255], v[254:255], v[162:163]
	v_pk_add_f32 v[32:33], v[32:33], v[252:253]
	v_pk_add_f32 v[34:35], v[34:35], v[254:255]
	v_cvt_pk_bf16_f32 v216, v32, v33
	v_cvt_pk_bf16_f32 v217, v34, v35
	v_lshlrev_b32_e32 v252, 16, v216
	v_and_b32_e32 v253, 0xffff0000, v216
	v_lshlrev_b32_e32 v254, 16, v217
	v_and_b32_e32 v255, 0xffff0000, v217
	v_pk_add_f32 v[32:33], v[32:33], v[252:253] neg_lo:[0,1] neg_hi:[0,1]
	v_pk_add_f32 v[34:35], v[34:35], v[254:255] neg_lo:[0,1] neg_hi:[0,1]
	v_cvt_pk_bf16_f32 v218, v32, v33
	v_cvt_pk_bf16_f32 v219, v34, v35
	global_store_dwordx2 v246, v[216:217], s[44:45] offset:96
	global_store_dwordx2 v246, v[218:219], s[52:53] offset:96
	s_mov_b64 exec, s[6:7]

; __device__ __forceinline__ void rem_tile(int pos, int& mt, int& nt) { if (pos < 65) { mt = pos; nt = 40; } else { mt = 64; nt = pos - 65; } }
;     ...
;     auto tile_end = [&]() {
;       float rs[TI];
; #pragma unroll
;       for (int ti = 0; ti < TI; ++ti) rs[ti] = 1.f;
;       if (RS) {
; #pragma unroll
;         for (int ti = 0; ti < TI; ++ti) rs[ti] = rsl[(ti < 4 ? wn * 64 + ti * 16 : 0) + lr];
;       }
;       int mt, nt; if (TMAP == 1) rem_tile(c_id, mt, nt); else tile_of(c_id, ntn, mt, nt);
;       const int tokb = mt * 2 * BMH + hh * BMH;
;       if (tokb < M_) gemm_epilogue<EPI, TI>(ws, acc, rs, tokb, nt * 128, wm, wn, lr, lq, dry);
; #pragma unroll
;       for (int a = 0; a < 4; ++a)
; #pragma unroll
;         for (int b = 0; b < TI; ++b) acc[a][b] = (f32x4){0.f, 0.f, 0.f, 0.f};
;       c_id += G;
;     };
;     issue(ra0, rb0, rx0);
;     issue(ra1, rb1, rx1);
;     store(ra0, rb0, rx0, 0);
;     __syncthreads();
; #pragma unroll 1
;     for (int s = 0; s < S; s += 2) {
;       issue(ra0, rb0, rx0);
;       compute(0);
;       store(ra1, rb1, rx1, 1);
;       __syncthreads();
;       issue(ra1, rb1, rx1);
;       compute(1);
;       c_kt += 2;
;       if (c_kt == nk) { c_kt = 0; tile_end(); }
;       store(ra0, rb0, rx0, 0);
;       __syncthreads();
;     }
.LBB0_980:
	s_load_dwordx2 s[4:5], s[0:1], 0x110
	v_mov_b32_e32 v14, v12
	v_mov_b32_e32 v15, v12
	v_mov_b32_e32 v13, v12
	v_mov_b32_e32 v139, 0
	v_mov_b64_e32 v[110:111], v[14:15]
	v_mov_b64_e32 v[90:91], v[14:15]
	v_mov_b64_e32 v[38:39], v[14:15]
	v_mov_b64_e32 v[34:35], v[14:15]
	s_waitcnt lgkmcnt(0)
	s_add_i32 s12, s12, s4
	s_lshr_b32 s100, s12, 6
	s_lshl_b32 s100, s100, 3
	s_and_b32 s101, s12, 7
	s_or_b32 s100, s100, s101
	s_mulk_i32 s100, 0x102
	s_add_i32 s100, s100, s30
	s_lshl_b32 s100, s100, 11
	s_bfe_u32 s101, s12, 0x30003
	s_lshl_b32 s101, s101, 8
	s_add_i32 s100, s100, s101
	s_mov_b32 s8, 0
	v_mov_b32_e32 v138, v139
	v_mov_b32_e32 v137, v139
	v_mov_b32_e32 v136, v139
	v_mov_b32_e32 v135, v139
	v_mov_b32_e32 v134, v139
	v_mov_b32_e32 v133, v139
	v_mov_b32_e32 v132, v139
	v_mov_b32_e32 v131, v139
	v_mov_b32_e32 v130, v139
	v_mov_b32_e32 v129, v139
	v_mov_b32_e32 v128, v139
	v_mov_b32_e32 v127, v139
	v_mov_b32_e32 v126, v139
	v_mov_b32_e32 v125, v139
	v_mov_b32_e32 v124, v139
	v_mov_b32_e32 v123, v139
	v_mov_b32_e32 v122, v139
	v_mov_b32_e32 v121, v139
	v_mov_b32_e32 v120, v139
	v_mov_b32_e32 v119, v139
	v_mov_b32_e32 v118, v139
	v_mov_b32_e32 v117, v139
	v_mov_b32_e32 v116, v139
	v_mov_b32_e32 v115, v139
	v_mov_b32_e32 v114, v139
	v_mov_b32_e32 v113, v139
	v_mov_b32_e32 v112, v139
	v_mov_b32_e32 v107, v139
	v_mov_b32_e32 v106, v139
	v_mov_b32_e32 v105, v139
	v_mov_b32_e32 v104, v139
	v_mov_b32_e32 v103, v139
	v_mov_b32_e32 v102, v139
	v_mov_b32_e32 v101, v139
	v_mov_b32_e32 v100, v139
	v_mov_b32_e32 v99, v139
	v_mov_b32_e32 v98, v139
	v_mov_b32_e32 v97, v139
	v_mov_b32_e32 v96, v139
	v_mov_b32_e32 v95, v139
	v_mov_b32_e32 v94, v139
	v_mov_b32_e32 v93, v139
	v_mov_b32_e32 v92, v139
	v_mov_b32_e32 v87, v139
	v_mov_b32_e32 v86, v139
	v_mov_b32_e32 v85, v139
	v_mov_b32_e32 v84, v139
	v_mov_b32_e32 v83, v139
	v_mov_b32_e32 v82, v139
	v_mov_b32_e32 v81, v139
	v_mov_b32_e32 v80, v139
	v_mov_b32_e32 v79, v139
	v_mov_b32_e32 v78, v139
	v_mov_b32_e32 v77, v139
	v_mov_b32_e32 v76, v139
	v_mov_b32_e32 v75, v139
	v_mov_b32_e32 v74, v139
	v_mov_b32_e32 v73, v139
	v_mov_b32_e32 v72, v139
	v_mov_b32_e32 v71, v139
	v_mov_b32_e32 v70, v139
	v_mov_b32_e32 v69, v139
	v_mov_b32_e32 v68, v139
	v_mov_b64_e32 v[108:109], v[12:13]
	v_mov_b64_e32 v[88:89], v[12:13]
	v_mov_b64_e32 v[36:37], v[12:13]
	v_mov_b64_e32 v[32:33], v[12:13]
.LBB0_981:
	s_waitcnt vmcnt(15)
	ds_write_b128 v178, v[40:43]
	s_waitcnt vmcnt(14)
	ds_write_b128 v178, v[44:47] offset:4096
	s_waitcnt vmcnt(13)
	ds_write_b128 v178, v[48:51] offset:8192
	s_waitcnt vmcnt(12)
	ds_write_b128 v178, v[52:55] offset:12288
	s_waitcnt vmcnt(11)
	ds_write_b128 v177, v[60:63] offset:32768
	s_waitcnt vmcnt(10)
	ds_write_b128 v177, v[64:67] offset:40960
	s_and_saveexec_b64 s[4:5], s[38:39]
	s_cbranch_execz .LBB0_938
	s_waitcnt vmcnt(9)
	ds_write_b128 v202, v[56:59]
	s_branch .LBB0_938

; __device__ __forceinline__ int half_id() { return __builtin_amdgcn_readfirstlane((int)(threadIdx.x >> 8)); }
; __device__ __forceinline__ int opaque_tid() { int t = threadIdx.x & 255; asm volatile("" : "+v"(t)); return t; }
; __device__ __forceinline__ int opaque_tid512() { int t = threadIdx.x; asm volatile("" : "+v"(t)); return t; }
;     ...
;   const int tid = opaque_tid(), lane = tid & 63, w = tid >> 6, wm = w >> 1, wn = w & 1, lr = lane & 15, lq = lane >> 4;
;   const int tid5 = opaque_tid512(), hh = half_id();
;   const int G = gridDim.x;
;   const int nk = K >> 6;
;   if (bid < ntiles) {
;     const int my_tiles = (ntiles - 1 - bid) / G + 1;
;     const int last_id = bid + (my_tiles - 1) * G;
;     const int S = my_tiles * nk;
;     f32x4 acc[4][TI];
; #pragma unroll
;     for (int a = 0; a < 4; ++a)
; #pragma unroll
;       for (int b = 0; b < TI; ++b) acc[a][b] = (f32x4){0.f, 0.f, 0.f, 0.f};
;     u32x4 ra0[4], rb0[2], ra1[4], rb1[2];
;     u32x4 rx0 = (u32x4){0u, 0u, 0u, 0u}, rx1 = (u32x4){0u, 0u, 0u, 0u};
;     float ss[5] = {0.f, 0.f, 0.f, 0.f, 0.f};
;     int l_id = bid, l_kt = 0, c_id = bid, c_kt = 0, st_kt = 0;
;     const int srow = tid >> 3;
;     const int soff = srow * 128 + (((tid & 7) ^ (srow & 7)) << 4);
;     const int wrow = tid5 >> 3;
;     const int woff = wrow * 128 + (((tid5 & 7) ^ (wrow & 7)) << 4);
.LBB0_1777:
	s_or_b64 exec, exec, s[6:7]
	s_lshl_b32 s31, s8, 5
	s_add_i32 s31, s31, 32
	s_cmp_lt_i32 s31, 1
	s_waitcnt lgkmcnt(0)
	s_barrier
	s_cbranch_scc1 .LBB0_1824
	v_and_b32_e32 v11, 15, v10
	v_ashrrev_i32_e32 v8, 7, v10
	v_bfe_u32 v9, v10, 6, 1
	v_lshlrev_b32_e32 v15, 7, v11
	v_lshrrev_b32_e32 v13, 4, v10
	v_lshl_or_b32 v37, v9, 13, v15
	v_lshl_or_b32 v180, v8, 13, v15
	v_and_b32_e32 v15, 7, v10
	v_bitop3_b32 v13, v13, v15, 3 bitop3:0x6c
	v_bfe_u32 v14, v10, 4, 2
	v_lshlrev_b32_e32 v181, 4, v13
	v_and_b32_e32 v13, 64, v10
	s_add_u32 s50, s44, 0x2040000
	v_cmp_ne_u32_e64 s[40:41], 0, v13
	v_or_b32_e32 v13, 4, v14
	v_bitop3_b32 v15, v14, v15, 4 bitop3:0x36
	v_lshlrev_b32_e32 v10, 4, v10
	s_addc_u32 s51, s45, 0
	v_add_u32_e32 v179, s9, v37
	v_lshlrev_b32_e32 v37, 4, v14
	v_lshlrev_b32_e32 v182, 4, v15
	v_lshlrev_b32_e32 v38, 4, v13
	v_and_b32_e32 v10, 0x70, v10
	v_lshlrev_b32_e32 v183, 6, v8
	v_lshlrev_b32_e32 v172, 2, v14
	v_or_b32_e32 v8, v9, v11
	v_mov_b32_e32 v13, v12
	v_mov_b32_e32 v14, v12
	v_mov_b32_e32 v15, v12
	s_add_u32 s54, s44, 0xa344000
	v_lshl_or_b32 v184, v9, 6, v11
	v_cmp_eq_u32_e32 vcc, 0, v11
	v_cmp_eq_u32_e64 s[42:43], 0, v8
	v_mov_b32_e32 v68, 0
	v_add_u32_e32 v185, v36, v37
	v_add_u32_e32 v201, v36, v38
	v_add_u32_e32 v202, v36, v10
	v_mov_b64_e32 v[8:9], v[12:13]
	v_mov_b64_e32 v[38:39], v[14:15]
	v_mov_b64_e32 v[90:91], v[14:15]
	v_mov_b64_e32 v[110:111], v[14:15]
	s_addc_u32 s55, s45, 0
	s_mov_b32 s56, 0
	s_mov_b32 s6, 2
	s_and_b64 s[52:53], vcc, s[40:41]
	v_mov_b64_e32 v[10:11], v[14:15]
	v_mov_b64_e32 v[36:37], v[12:13]
	v_mov_b64_e32 v[88:89], v[12:13]
	v_mov_b64_e32 v[108:109], v[12:13]
	s_mov_b32 s8, 0
	s_mov_b32 s7, s12
	v_mov_b32_e32 v69, v68
	v_mov_b32_e32 v70, v68
	v_mov_b32_e32 v71, v68
	v_mov_b32_e32 v72, v68
	v_mov_b32_e32 v73, v68
	v_mov_b32_e32 v74, v68
	v_mov_b32_e32 v75, v68
	v_mov_b32_e32 v76, v68
	v_mov_b32_e32 v77, v68
	v_mov_b32_e32 v78, v68
	v_mov_b32_e32 v79, v68
	v_mov_b32_e32 v80, v68
	v_mov_b32_e32 v81, v68
	v_mov_b32_e32 v82, v68
	v_mov_b32_e32 v83, v68
	v_mov_b32_e32 v84, v68
	v_mov_b32_e32 v85, v68
	v_mov_b32_e32 v86, v68
	v_mov_b32_e32 v87, v68
	v_mov_b32_e32 v92, v68
	v_mov_b32_e32 v93, v68
	v_mov_b32_e32 v94, v68
	v_mov_b32_e32 v95, v68
	v_mov_b32_e32 v96, v68
	v_mov_b32_e32 v97, v68
	v_mov_b32_e32 v98, v68
	v_mov_b32_e32 v99, v68
	v_mov_b32_e32 v100, v68
	v_mov_b32_e32 v101, v68
	v_mov_b32_e32 v102, v68
	v_mov_b32_e32 v103, v68
	v_mov_b32_e32 v104, v68
	v_mov_b32_e32 v105, v68
	v_mov_b32_e32 v106, v68
	v_mov_b32_e32 v107, v68
	v_mov_b32_e32 v112, v68
	v_mov_b32_e32 v113, v68
	v_mov_b32_e32 v114, v68
	v_mov_b32_e32 v115, v68
	v_mov_b32_e32 v116, v68
	v_mov_b32_e32 v117, v68
	v_mov_b32_e32 v118, v68
	v_mov_b32_e32 v119, v68
	v_mov_b32_e32 v120, v68
	v_mov_b32_e32 v121, v68
	v_mov_b32_e32 v122, v68
	v_mov_b32_e32 v123, v68
	v_mov_b32_e32 v124, v68
	v_mov_b32_e32 v125, v68
	v_mov_b32_e32 v126, v68
	v_mov_b32_e32 v127, v68
	v_mov_b32_e32 v128, v68
	v_mov_b32_e32 v129, v68
	v_mov_b32_e32 v130, v68
	v_mov_b32_e32 v131, v68
	v_mov_b32_e32 v132, v68
	v_mov_b32_e32 v133, v68
	v_mov_b32_e32 v134, v68
	v_mov_b32_e32 v135, v68
	v_mov_b32_e32 v136, v68
	v_mov_b32_e32 v137, v68
	v_mov_b32_e32 v138, v68
	v_mov_b32_e32 v139, v68
	s_lshr_b32 s100, s12, 6
	s_lshl_b32 s100, s100, 3
	s_and_b32 s101, s12, 7
	s_or_b32 s100, s100, s101
	s_mulk_i32 s100, 0x102
	s_add_i32 s100, s100, s30
	s_lshl_b32 s100, s100, 11
	s_bfe_u32 s101, s12, 0x30003
	s_lshl_b32 s101, s101, 8
	s_add_i32 s100, s100, s101
	v_mbcnt_lo_u32_b32 v251, -1, 0
	v_mbcnt_hi_u32_b32 v251, -1, v251
	v_and_b32_e32 v251, 7, v251
	v_and_b32_e32 v250, 64, v184
	v_add_u32_e32 v251, v250, v251
	v_lshlrev_b32_e32 v250, 1, v183
	v_lshl_add_u32 v251, v251, 11, v250
	global_load_dword v249, v12, s[50:51]
	s_branch .LBB0_1780

; #define MFMA16(a, b, c) __builtin_amdgcn_mfma_f32_16x16x32_bf16((a), (b), (c), 0, 0, 0)
;     ...
;     auto issue = [&](u32x4 (&ra)[4], u32x4 (&rb)[2], u32x4& rx) {
;       const int idc = l_id < last_id ? l_id : last_id;
;       int mt, nt; if (TMAP == 1) rem_tile(idc, mt, nt); else tile_of(idc, ntn, mt, nt);
;       const bf16_t* A = (l_kt < ktsplit) ? A0 : A1;
;       const int kk = (l_kt < ktsplit) ? l_kt : l_kt - ktsplit;
;       const int arow = mt * 2 * BMH + hh * BMH + srow;
;       const bf16_t* akb = A + kk * kstride + (tid & 7) * 8;
;       const bf16_t* wp = W + (size_t)(nt * 128 + wrow) * K + l_kt * 64 + (tid5 & 7) * 8;
; #pragma unroll
;       for (int i = 0; i < 4; ++i) {
;         int r = arow + 32 * i; r = r < M_ ? r : M_ - 1;
;         ra[i] = *(const u32x4*)(akb + (size_t)r * lda);
;       }
; #pragma unroll
;       for (int i = 0; i < 2; ++i) rb[i] = *(const u32x4*)(wp + (size_t)i * 64 * K);
;       if (TI == 5) rx = *(const u32x4*)(akb + (size_t)(arow - srow + 128) * lda);
;       if (++l_kt == nk) { l_kt = 0; l_id += G; }
;     };
;     ...
;     auto compute = [&](int buf) {
;       const unsigned char* Ab = As + buf * ASTG + (wn * 64 + lr) * 128;
;       const unsigned char* Ax = Ax0 + buf * 128;
;       const unsigned char* Bb = Bs + buf * 16384 + (wm * 64 + lr) * 128;
; #pragma unroll
;       for (int ks = 0; ks < 2; ++ks) {
;         if (TI == 5 && ks == 1) __builtin_amdgcn_sched_barrier(0);
;         const int sw = ((ks * 4 + lq) ^ (lr & 7)) << 4;
;         bf16x8 wf[4], xf[TI];
; #pragma unroll
;         for (int i = 0; i < 4; ++i) {
;           wf[i] = *(const bf16x8*)(Bb + i * 2048 + sw);
;           xf[i] = *(const bf16x8*)(Ab + i * 2048 + sw);
;         }
;         if (TI == 5) xf[TI - 1] = *(const bf16x8*)(Ax + ((ks * 4 + lq) << 4));
; #pragma unroll
;         for (int ni = 0; ni < 4; ++ni)
; #pragma unroll
;           for (int ti = 0; ti < 4; ++ti) acc[ni][ti] = MFMA16(wf[ni], xf[ti], acc[ni][ti]);
;         if (TI == 5) {
;           if (wn == 0) { acc[0][TI - 1] = MFMA16(wf[0], xf[TI - 1], acc[0][TI - 1]); acc[1][TI - 1] = MFMA16(wf[1], xf[TI - 1], acc[1][TI - 1]); }
;           else { acc[2][TI - 1] = MFMA16(wf[2], xf[TI - 1], acc[2][TI - 1]); acc[3][TI - 1] = MFMA16(wf[3], xf[TI - 1], acc[3][TI - 1]); }
;         }
;       }
;     };
.LBB0_1784:
	s_cmp_lt_i32 s6, 16
	s_cselect_b32 s5, 0, -16
	s_cselect_b32 s10, s47, s55
	s_cselect_b32 s11, s46, s54
	s_add_i32 s5, s5, s6
	v_add_u32_e32 v13, v180, v181
	v_add_u32_e32 v14, s4, v176
	s_lshl_b32 s4, s5, 6
	ds_read_b128 v[148:151], v13 offset:32768
	s_ashr_i32 s5, s4, 31
	s_lshl_b64 s[4:5], s[4:5], 1
	s_add_u32 s4, s11, s4
	v_add_u32_e32 v15, v179, v181
	v_min_i32_e32 v42, 0x405f, v14
	s_addc_u32 s5, s10, s5
	v_mov_b32_e32 v169, v12
	ds_read_b128 v[56:59], v15
	ds_read_b128 v[152:155], v13 offset:34816
	s_waitcnt vmcnt(8)
	ds_read_b128 v[64:67], v15 offset:2048
	ds_read_b128 v[160:163], v15 offset:4096
	ds_read_b128 v[204:207], v15 offset:6144
	v_ashrrev_i32_e32 v43, 31, v42
	v_lshl_add_u64 v[208:209], s[4:5], 0, v[168:169]
	v_min_i32_e32 v40, 0x407f, v14
	v_lshlrev_b64 v[42:43], 11, v[42:43]
	v_ashrrev_i32_e32 v41, 31, v40
	v_lshl_add_u64 v[42:43], v[208:209], 0, v[42:43]
	v_lshlrev_b64 v[40:41], 11, v[40:41]
	v_add_co_u32_e32 v44, vcc, s82, v42
	v_lshl_add_u64 v[40:41], v[208:209], 0, v[40:41]
	s_nop 0
	v_addc_co_u32_e32 v45, vcc, 0, v43, vcc
	s_waitcnt lgkmcnt(1)
	v_mfma_f32_16x16x32_bf16 v[140:143], v[148:151], v[160:163], v[128:131]
	global_load_dwordx4 v[40:43], v[40:41], off
	s_nop 0
	global_load_dwordx4 v[44:47], v[44:45], off
	ds_read_b128 v[128:131], v13 offset:36864
	ds_read_b128 v[156:159], v13 offset:38912
	v_min_i32_e32 v48, 0x403f, v14
	v_ashrrev_i32_e32 v49, 31, v48
	v_lshl_add_u32 v60, s9, 7, v174
	v_lshlrev_b64 v[48:49], 11, v[48:49]
	v_min_i32_e32 v50, 0x401f, v14
	v_ashrrev_i32_e32 v61, 31, v60
	v_lshl_add_u64 v[48:49], v[208:209], 0, v[48:49]
	v_ashrrev_i32_e32 v51, 31, v50
	s_lshl_b32 s4, s6, 6
	v_add_co_u32_e32 v48, vcc, s2, v48
	v_lshlrev_b64 v[50:51], 11, v[50:51]
	v_lshlrev_b64 v[60:61], 12, v[60:61]
	s_ashr_i32 s5, s4, 31
	v_addc_co_u32_e32 v49, vcc, 0, v49, vcc
	v_lshl_add_u64 v[50:51], v[208:209], 0, v[50:51]
	s_mov_b32 s3, 0x30000
	v_lshl_add_u64 v[60:61], s[48:49], 0, v[60:61]
	v_sub_u32_e32 v14, v14, v173
	s_waitcnt lgkmcnt(1)
	v_mfma_f32_16x16x32_bf16 v[144:147], v[128:131], v[56:59], v[100:103]
	v_add_co_u32_e32 v52, vcc, s3, v50
	v_lshl_add_u64 v[60:61], s[4:5], 1, v[60:61]
	v_mov_b32_e32 v171, v12
	v_add_u32_e32 v100, 0x80, v14
	v_addc_co_u32_e32 v53, vcc, 0, v51, vcc
	v_lshl_add_u64 v[60:61], v[60:61], 0, v[170:171]
	s_mov_b32 s3, 0x40000
	v_ashrrev_i32_e32 v101, 31, v100
	v_mfma_f32_16x16x32_bf16 v[132:135], v[148:151], v[64:67], v[132:135]
	v_add_co_u32_e32 v62, vcc, s3, v60
	global_load_dwordx4 v[48:51], v[48:49], off
	s_nop 0
	global_load_dwordx4 v[52:55], v[52:53], off
	v_mfma_f32_16x16x32_bf16 v[116:119], v[152:155], v[64:67], v[116:119]
	v_addc_co_u32_e32 v63, vcc, 0, v61, vcc
	v_mfma_f32_16x16x32_bf16 v[96:99], v[128:131], v[64:67], v[96:99]
	s_waitcnt lgkmcnt(0)
	v_mfma_f32_16x16x32_bf16 v[76:79], v[156:159], v[64:67], v[76:79]
	v_lshlrev_b64 v[64:65], 11, v[100:101]
	v_lshl_add_u64 v[64:65], v[208:209], 0, v[64:65]
	v_mfma_f32_16x16x32_bf16 v[136:139], v[148:151], v[56:59], v[136:139]
	v_mfma_f32_16x16x32_bf16 v[120:123], v[152:155], v[56:59], v[120:123]
	v_mfma_f32_16x16x32_bf16 v[80:83], v[156:159], v[56:59], v[80:83]
	global_load_dwordx4 v[56:59], v[60:61], off
	s_nop 0
	global_load_dwordx4 v[60:63], v[62:63], off
	ds_read_b128 v[100:103], v185
	global_load_dwordx4 v[64:67], v[64:65], off
	s_sub_u32 s101, s8, 14
	s_lshr_b32 s101, s101, 1
	s_lshl_b32 s101, s101, 14
	s_add_u32 s101, s101, s100
	v_add_u32_e32 v250, s101, v251
	s_sub_u32 s101, s8, 14
	s_cmp_le_u32 s101, 14
	s_cselect_b32 s101, -1, 0
	v_and_b32_e32 v250, s101, v250
	global_load_dword v249, v250, s[44:45]
	v_mfma_f32_16x16x32_bf16 v[124:127], v[148:151], v[204:207], v[124:127]
	v_mfma_f32_16x16x32_bf16 v[112:115], v[152:155], v[160:163], v[112:115]
	v_mfma_f32_16x16x32_bf16 v[104:107], v[152:155], v[204:207], v[104:107]
	v_mfma_f32_16x16x32_bf16 v[92:95], v[128:131], v[160:163], v[92:95]
	v_mfma_f32_16x16x32_bf16 v[84:87], v[128:131], v[204:207], v[84:87]
	v_mfma_f32_16x16x32_bf16 v[72:75], v[156:159], v[160:163], v[72:75]
	v_mfma_f32_16x16x32_bf16 v[68:71], v[156:159], v[204:207], v[68:71]
	s_and_saveexec_b64 s[4:5], s[40:41]
	s_xor_b64 s[4:5], exec, s[4:5]
	s_cbranch_execz .LBB0_1786
	s_waitcnt lgkmcnt(0)
	v_mfma_f32_16x16x32_bf16 v[36:39], v[128:131], v[100:103], v[36:39]
	v_mfma_f32_16x16x32_bf16 v[8:11], v[156:159], v[100:103], v[8:11]

;     ...
;     auto store = [&](const u32x4 (&ra)[4], const u32x4 (&rb)[2], const u32x4& rx, int buf) {
; #pragma unroll
;       for (int i = 0; i < 4; ++i) {
;         if (RS) ss[i] += sumsq8(__builtin_bit_cast(bf16x8, ra[i]));
;         *(u32x4*)(As + buf * ASTG + i * 4096 + soff) = ra[i];
;       }
; #pragma unroll
;       for (int i = 0; i < 2; ++i) *(u32x4*)(Bs + buf * 16384 + i * 8192 + woff) = rb[i];
;       if (TI == 5) {
;         if (RS) ss[4] += sumsq8(__builtin_bit_cast(bf16x8, rx));
;         if (srow == 0) *(u32x4*)(Ax0 + buf * 128 + ((tid & 7) << 4)) = rx;
;       }
.LBB0_1792:
	s_or_b64 exec, exec, s[4:5]
	s_waitcnt vmcnt(15)
	ds_write_b128 v178, v[0:3] offset:16384
	s_waitcnt vmcnt(14)
	ds_write_b128 v178, v[4:7] offset:20480
	s_waitcnt vmcnt(13)
	ds_write_b128 v178, v[16:19] offset:24576
	s_waitcnt vmcnt(12)
	ds_write_b128 v178, v[20:23] offset:28672
	s_waitcnt vmcnt(11)
	ds_write_b128 v177, v[24:27] offset:49152
	s_waitcnt vmcnt(10)
	ds_write_b128 v177, v[28:31] offset:57344
	s_and_saveexec_b64 s[4:5], s[38:39]
	s_cbranch_execz .LBB0_1794
	s_waitcnt vmcnt(9)
	ds_write_b128 v202, v[32:35] offset:128

; #define MFMA16(a, b, c) __builtin_amdgcn_mfma_f32_16x16x32_bf16((a), (b), (c), 0, 0, 0)
;     ...
;     auto issue = [&](u32x4 (&ra)[4], u32x4 (&rb)[2], u32x4& rx) {
;       const int idc = l_id < last_id ? l_id : last_id;
;       int mt, nt; if (TMAP == 1) rem_tile(idc, mt, nt); else tile_of(idc, ntn, mt, nt);
;       const bf16_t* A = (l_kt < ktsplit) ? A0 : A1;
;       const int kk = (l_kt < ktsplit) ? l_kt : l_kt - ktsplit;
;       const int arow = mt * 2 * BMH + hh * BMH + srow;
;       const bf16_t* akb = A + kk * kstride + (tid & 7) * 8;
;       const bf16_t* wp = W + (size_t)(nt * 128 + wrow) * K + l_kt * 64 + (tid5 & 7) * 8;
; #pragma unroll
;       for (int i = 0; i < 4; ++i) {
;         int r = arow + 32 * i; r = r < M_ ? r : M_ - 1;
;         ra[i] = *(const u32x4*)(akb + (size_t)r * lda);
;       }
; #pragma unroll
;       for (int i = 0; i < 2; ++i) rb[i] = *(const u32x4*)(wp + (size_t)i * 64 * K);
;       if (TI == 5) rx = *(const u32x4*)(akb + (size_t)(arow - srow + 128) * lda);
;       if (++l_kt == nk) { l_kt = 0; l_id += G; }
;     };
;     ...
;     auto compute = [&](int buf) {
;       const unsigned char* Ab = As + buf * ASTG + (wn * 64 + lr) * 128;
;       const unsigned char* Ax = Ax0 + buf * 128;
;       const unsigned char* Bb = Bs + buf * 16384 + (wm * 64 + lr) * 128;
; #pragma unroll
;       for (int ks = 0; ks < 2; ++ks) {
;         if (TI == 5 && ks == 1) __builtin_amdgcn_sched_barrier(0);
;         const int sw = ((ks * 4 + lq) ^ (lr & 7)) << 4;
;         bf16x8 wf[4], xf[TI];
; #pragma unroll
;         for (int i = 0; i < 4; ++i) {
;           wf[i] = *(const bf16x8*)(Bb + i * 2048 + sw);
;           xf[i] = *(const bf16x8*)(Ab + i * 2048 + sw);
;         }
;         if (TI == 5) xf[TI - 1] = *(const bf16x8*)(Ax + ((ks * 4 + lq) << 4));
; #pragma unroll
;         for (int ni = 0; ni < 4; ++ni)
; #pragma unroll
;           for (int ti = 0; ti < 4; ++ti) acc[ni][ti] = MFMA16(wf[ni], xf[ti], acc[ni][ti]);
;         if (TI == 5) {
;           if (wn == 0) { acc[0][TI - 1] = MFMA16(wf[0], xf[TI - 1], acc[0][TI - 1]); acc[1][TI - 1] = MFMA16(wf[1], xf[TI - 1], acc[1][TI - 1]); }
;           else { acc[2][TI - 1] = MFMA16(wf[2], xf[TI - 1], acc[2][TI - 1]); acc[3][TI - 1] = MFMA16(wf[3], xf[TI - 1], acc[3][TI - 1]); }
;         }
;       }
;     };
.LBB0_1798:
	s_and_b64 s[4:5], s[4:5], exec
	s_cselect_b32 s58, 0, s10
	s_cmp_lt_i32 s58, 16
	s_cselect_b32 s4, 0, -16
	s_cselect_b32 s7, s47, s55
	s_cselect_b32 s10, s46, s54
	s_add_i32 s4, s4, s58
	s_lshl_b32 s4, s4, 6
	ds_read_b128 v[148:151], v13 offset:49152
	ds_read_b128 v[24:27], v15 offset:16384
	s_ashr_i32 s5, s4, 31
	v_add_u32_e32 v210, s6, v176
	s_lshl_b64 s[4:5], s[4:5], 1
	s_add_u32 s4, s10, s4
	v_min_i32_e32 v2, 0x405f, v210
	s_addc_u32 s5, s7, s5
	v_mov_b32_e32 v169, v12
	ds_read_b128 v[152:155], v13 offset:51200
	s_waitcnt vmcnt(8)
	ds_read_b128 v[32:35], v15 offset:18432
	ds_read_b128 v[160:163], v15 offset:20480
	ds_read_b128 v[204:207], v15 offset:22528
	v_ashrrev_i32_e32 v3, 31, v2
	v_lshl_add_u64 v[208:209], s[4:5], 0, v[168:169]
	v_min_i32_e32 v0, 0x407f, v210
	v_lshlrev_b64 v[2:3], 11, v[2:3]
	v_ashrrev_i32_e32 v1, 31, v0
	v_lshl_add_u64 v[2:3], v[208:209], 0, v[2:3]
	v_lshlrev_b64 v[0:1], 11, v[0:1]
	v_add_co_u32_e32 v4, vcc, s82, v2
	v_lshl_add_u64 v[0:1], v[208:209], 0, v[0:1]
	s_nop 0
	v_addc_co_u32_e32 v5, vcc, 0, v3, vcc
	s_waitcnt lgkmcnt(1)
	v_mfma_f32_16x16x32_bf16 v[140:143], v[148:151], v[160:163], v[132:135]
	global_load_dwordx4 v[0:3], v[0:1], off
	s_nop 0
	global_load_dwordx4 v[4:7], v[4:5], off
	ds_read_b128 v[132:135], v13 offset:53248
	ds_read_b128 v[156:159], v13 offset:55296
	v_min_i32_e32 v16, 0x403f, v210
	v_ashrrev_i32_e32 v17, 31, v16
	v_lshl_add_u32 v28, s9, 7, v174
	v_lshlrev_b64 v[16:17], 11, v[16:17]
	v_min_i32_e32 v18, 0x401f, v210
	v_ashrrev_i32_e32 v29, 31, v28
	v_lshl_add_u64 v[16:17], v[208:209], 0, v[16:17]
	v_ashrrev_i32_e32 v19, 31, v18
	s_lshl_b32 s4, s58, 6
	v_add_co_u32_e32 v16, vcc, s2, v16
	v_lshlrev_b64 v[18:19], 11, v[18:19]
	v_lshlrev_b64 v[28:29], 12, v[28:29]
	s_ashr_i32 s5, s4, 31
	v_addc_co_u32_e32 v17, vcc, 0, v17, vcc
	v_lshl_add_u64 v[18:19], v[208:209], 0, v[18:19]
	s_mov_b32 s3, 0x30000
	v_lshl_add_u64 v[28:29], s[48:49], 0, v[28:29]
	v_sub_u32_e32 v13, v210, v173
	s_waitcnt lgkmcnt(1)
	v_mfma_f32_16x16x32_bf16 v[144:147], v[132:135], v[24:27], v[104:107]
	v_add_co_u32_e32 v20, vcc, s3, v18
	v_lshl_add_u64 v[28:29], s[4:5], 1, v[28:29]
	v_mov_b32_e32 v171, v12
	v_add_u32_e32 v104, 0x80, v13
	v_addc_co_u32_e32 v21, vcc, 0, v19, vcc
	v_lshl_add_u64 v[28:29], v[28:29], 0, v[170:171]
	s_mov_b32 s3, 0x40000
	v_ashrrev_i32_e32 v105, 31, v104
	v_mfma_f32_16x16x32_bf16 v[128:131], v[148:151], v[32:35], v[128:131]
	v_add_co_u32_e32 v30, vcc, s3, v28
	global_load_dwordx4 v[16:19], v[16:17], off
	s_nop 0
	global_load_dwordx4 v[20:23], v[20:21], off
	v_mfma_f32_16x16x32_bf16 v[116:119], v[152:155], v[32:35], v[116:119]
	v_addc_co_u32_e32 v31, vcc, 0, v29, vcc
	v_mfma_f32_16x16x32_bf16 v[96:99], v[132:135], v[32:35], v[96:99]
	s_waitcnt lgkmcnt(0)
	v_mfma_f32_16x16x32_bf16 v[76:79], v[156:159], v[32:35], v[76:79]
	v_lshlrev_b64 v[32:33], 11, v[104:105]
	v_lshl_add_u64 v[32:33], v[208:209], 0, v[32:33]
	v_mfma_f32_16x16x32_bf16 v[136:139], v[148:151], v[24:27], v[136:139]
	v_mfma_f32_16x16x32_bf16 v[120:123], v[152:155], v[24:27], v[120:123]
	v_mfma_f32_16x16x32_bf16 v[80:83], v[156:159], v[24:27], v[80:83]
	global_load_dwordx4 v[24:27], v[28:29], off
	s_nop 0
	global_load_dwordx4 v[28:31], v[30:31], off
	ds_read_b128 v[104:107], v185 offset:128
	global_load_dwordx4 v[32:35], v[32:33], off
	s_sub_u32 s101, s8, 14
	s_lshr_b32 s101, s101, 1
	s_lshl_b32 s101, s101, 14
	s_add_u32 s101, s101, s100
	v_add_u32_e32 v250, s101, v251
	s_sub_u32 s101, s8, 14
	s_cmp_le_u32 s101, 14
	s_cselect_b32 s101, -1, 0
	v_and_b32_e32 v250, s101, v250
	global_load_dword v249, v250, s[50:51]
	v_mfma_f32_16x16x32_bf16 v[124:127], v[148:151], v[204:207], v[124:127]
	v_mfma_f32_16x16x32_bf16 v[112:115], v[152:155], v[160:163], v[112:115]
	v_mfma_f32_16x16x32_bf16 v[100:103], v[152:155], v[204:207], v[100:103]
	v_mfma_f32_16x16x32_bf16 v[92:95], v[132:135], v[160:163], v[92:95]
	v_mfma_f32_16x16x32_bf16 v[84:87], v[132:135], v[204:207], v[84:87]
	v_mfma_f32_16x16x32_bf16 v[72:75], v[156:159], v[160:163], v[72:75]
	v_mfma_f32_16x16x32_bf16 v[68:71], v[156:159], v[204:207], v[68:71]
	s_and_saveexec_b64 s[4:5], s[40:41]
	s_xor_b64 s[4:5], exec, s[4:5]
	s_cbranch_execz .LBB0_1800
	s_waitcnt lgkmcnt(0)
	v_mfma_f32_16x16x32_bf16 v[36:39], v[132:135], v[104:107], v[36:39]
	v_mfma_f32_16x16x32_bf16 v[8:11], v[156:159], v[104:107], v[8:11]

; __device__ __forceinline__ float bflo(unsigned v) { return __uint_as_float(v << 16); }
; __device__ __forceinline__ float bfhi(unsigned v) { return __uint_as_float(v & 0xffff0000u); }
; template <int EPI, int TI>
; __device__ __forceinline__ void gemm_epilogue(const WS& ws, const f32x4 (&acc)[4][TI], const float (&rs)[TI], int tok0, int n0,
;                                               int wm, int wn, int lr, int lq, bool dry) {
;     ...
;   } else {
; #pragma unroll
;     for (int ni = 0; ni < 4; ++ni)
; #pragma unroll
;       for (int ti = 0; ti < TI; ++ti) {
;         if (!(ti < 4 || (lr == 0 && (ni >> 1) == wn))) continue;
;         const size_t off = (size_t)(ti < 4 ? tokr(ti) : tok0 + 128) * 1024 + nw + ni * 16 + 4 * lq;
;         const u32x2 hi = *(const u32x2*)(ws.HHI + off), lo = *(const u32x2*)(ws.HLO + off);
;         const float h0 = bflo(hi.x) + bflo(lo.x) + acc[ni][ti][0], h1 = bfhi(hi.x) + bfhi(lo.x) + acc[ni][ti][1];
;         const float h2 = bflo(hi.y) + bflo(lo.y) + acc[ni][ti][2], h3 = bfhi(hi.y) + bfhi(lo.y) + acc[ni][ti][3];
;         u32x2 nh; nh.x = cvt_pk_bf16(h0, h1); nh.y = cvt_pk_bf16(h2, h3);
;         u32x2 nl; nl.x = cvt_pk_bf16(h0 - bflo(nh.x), h1 - bfhi(nh.x)); nl.y = cvt_pk_bf16(h2 - bflo(nh.y), h3 - bfhi(nh.y));
;         if (!dry) { *(u32x2*)(ws.HHI + off) = nh; *(u32x2*)(ws.HLO + off) = nl; }
;       }
.LBB0_1812:
	s_waitcnt lgkmcnt(0)
	v_mbcnt_lo_u32_b32 v13, -1, 0
	v_mbcnt_hi_u32_b32 v13, -1, v13
	s_add_i32 s5, s4, 0x80
	v_and_b32_e32 v14, 3, v13
	v_lshrrev_b32_e32 v13, 2, v13
	s_lshl_b32 s5, s5, 11
	v_lshl_add_u32 v15, v14, 4, v13
	v_and_b32_e32 v247, 64, v184
	v_lshlrev_b32_e32 v15, 2, v15
	v_add3_u32 v13, s4, v247, v13
	v_lshl_add_u32 v247, s6, 7, v183
	s_mov_b64 s[6:7], exec
	v_lshl_add_u32 v14, v14, 2, v247
	v_or_b32_e32 v247, v247, v172
	v_lshlrev_b32_e32 v14, 1, v14
	v_lshlrev_b32_e32 v247, 1, v247
	v_lshl_add_u32 v242, v13, 11, v14
	v_add_u32_e32 v246, s5, v247
	v_add_u32_e32 v243, 0x8000, v242
	v_add_u32_e32 v244, 0x10000, v242
	v_add_u32_e32 v245, 0x18000, v242
	s_and_b64 exec, s[6:7], s[42:43]
	global_load_dwordx2 v[204:205], v246, s[44:45]
	global_load_dwordx2 v[206:207], v246, s[50:51]
	global_load_dwordx2 v[208:209], v246, s[44:45] offset:32
	global_load_dwordx2 v[210:211], v246, s[50:51] offset:32
	s_and_b64 exec, s[6:7], s[52:53]
	global_load_dwordx2 v[212:213], v246, s[44:45] offset:64
	global_load_dwordx2 v[214:215], v246, s[50:51] offset:64
	global_load_dwordx2 v[216:217], v246, s[44:45] offset:96
	global_load_dwordx2 v[218:219], v246, s[50:51] offset:96
	s_mov_b64 exec, s[6:7]
	global_load_dwordx2 v[140:141], v242, s[44:45]
	global_load_dwordx2 v[142:143], v242, s[50:51]
	global_load_dwordx2 v[144:145], v242, s[44:45] offset:32
	global_load_dwordx2 v[146:147], v242, s[50:51] offset:32
	global_load_dwordx2 v[148:149], v242, s[44:45] offset:64
	global_load_dwordx2 v[150:151], v242, s[50:51] offset:64
	global_load_dwordx2 v[152:153], v242, s[44:45] offset:96
	global_load_dwordx2 v[154:155], v242, s[50:51] offset:96
	global_load_dwordx2 v[156:157], v243, s[44:45]
	global_load_dwordx2 v[158:159], v243, s[50:51]
	ds_bpermute_b32 v136, v15, v136
	ds_bpermute_b32 v137, v15, v137
	ds_bpermute_b32 v138, v15, v138
	ds_bpermute_b32 v139, v15, v139
	ds_bpermute_b32 v120, v15, v120
	ds_bpermute_b32 v121, v15, v121
	ds_bpermute_b32 v122, v15, v122
	ds_bpermute_b32 v123, v15, v123
	ds_bpermute_b32 v100, v15, v100
	ds_bpermute_b32 v101, v15, v101
	ds_bpermute_b32 v102, v15, v102
	ds_bpermute_b32 v103, v15, v103
	s_waitcnt vmcnt(8)
	s_waitcnt lgkmcnt(8)
	v_lshlrev_b32_e32 v252, 16, v140
	v_and_b32_e32 v253, 0xffff0000, v140
	v_lshlrev_b32_e32 v160, 16, v142
	v_and_b32_e32 v161, 0xffff0000, v142
	v_lshlrev_b32_e32 v254, 16, v141
	v_and_b32_e32 v255, 0xffff0000, v141
	v_lshlrev_b32_e32 v162, 16, v143
	v_and_b32_e32 v163, 0xffff0000, v143
	v_pk_add_f32 v[252:253], v[252:253], v[160:161]
	v_pk_add_f32 v[254:255], v[254:255], v[162:163]
	v_pk_add_f32 v[136:137], v[136:137], v[252:253]
	v_pk_add_f32 v[138:139], v[138:139], v[254:255]
	v_cvt_pk_bf16_f32 v140, v136, v137
	v_cvt_pk_bf16_f32 v141, v138, v139
	v_lshlrev_b32_e32 v252, 16, v140
	v_and_b32_e32 v253, 0xffff0000, v140
	v_lshlrev_b32_e32 v254, 16, v141
	v_and_b32_e32 v255, 0xffff0000, v141
	v_pk_add_f32 v[136:137], v[136:137], v[252:253] neg_lo:[0,1] neg_hi:[0,1]
	v_pk_add_f32 v[138:139], v[138:139], v[254:255] neg_lo:[0,1] neg_hi:[0,1]
	v_cvt_pk_bf16_f32 v142, v136, v137
	v_cvt_pk_bf16_f32 v143, v138, v139
	global_store_dwordx2 v242, v[140:141], s[44:45]
	global_store_dwordx2 v242, v[142:143], s[50:51]
	global_load_dwordx2 v[140:141], v243, s[44:45] offset:32
	global_load_dwordx2 v[142:143], v243, s[50:51] offset:32
	ds_bpermute_b32 v80, v15, v80
	ds_bpermute_b32 v81, v15, v81
	ds_bpermute_b32 v82, v15, v82
	ds_bpermute_b32 v83, v15, v83
	s_waitcnt vmcnt(10)
	s_waitcnt lgkmcnt(8)
	v_lshlrev_b32_e32 v252, 16, v144
	v_and_b32_e32 v253, 0xffff0000, v144
	v_lshlrev_b32_e32 v160, 16, v146
	v_and_b32_e32 v161, 0xffff0000, v146
	v_lshlrev_b32_e32 v254, 16, v145
	v_and_b32_e32 v255, 0xffff0000, v145
	v_lshlrev_b32_e32 v162, 16, v147
	v_and_b32_e32 v163, 0xffff0000, v147
	v_pk_add_f32 v[252:253], v[252:253], v[160:161]
	v_pk_add_f32 v[254:255], v[254:255], v[162:163]
	v_pk_add_f32 v[120:121], v[120:121], v[252:253]
	v_pk_add_f32 v[122:123], v[122:123], v[254:255]
	v_cvt_pk_bf16_f32 v144, v120, v121
	v_cvt_pk_bf16_f32 v145, v122, v123
	v_lshlrev_b32_e32 v252, 16, v144
	v_and_b32_e32 v253, 0xffff0000, v144
	v_lshlrev_b32_e32 v254, 16, v145
	v_and_b32_e32 v255, 0xffff0000, v145
	v_pk_add_f32 v[120:121], v[120:121], v[252:253] neg_lo:[0,1] neg_hi:[0,1]
	v_pk_add_f32 v[122:123], v[122:123], v[254:255] neg_lo:[0,1] neg_hi:[0,1]
	v_cvt_pk_bf16_f32 v146, v120, v121
	v_cvt_pk_bf16_f32 v147, v122, v123
	global_store_dwordx2 v242, v[144:145], s[44:45] offset:32
	global_store_dwordx2 v242, v[146:147], s[50:51] offset:32
	global_load_dwordx2 v[144:145], v243, s[44:45] offset:64
	global_load_dwordx2 v[146:147], v243, s[50:51] offset:64
	ds_bpermute_b32 v132, v15, v132
	ds_bpermute_b32 v133, v15, v133
	ds_bpermute_b32 v134, v15, v134
	ds_bpermute_b32 v135, v15, v135
	s_waitcnt vmcnt(12)
	s_waitcnt lgkmcnt(8)
	v_lshlrev_b32_e32 v252, 16, v148
	v_and_b32_e32 v253, 0xffff0000, v148
	v_lshlrev_b32_e32 v160, 16, v150
	v_and_b32_e32 v161, 0xffff0000, v150
	v_lshlrev_b32_e32 v254, 16, v149
	v_and_b32_e32 v255, 0xffff0000, v149
	v_lshlrev_b32_e32 v162, 16, v151
	v_and_b32_e32 v163, 0xffff0000, v151
	v_pk_add_f32 v[252:253], v[252:253], v[160:161]
	v_pk_add_f32 v[254:255], v[254:255], v[162:163]
	v_pk_add_f32 v[100:101], v[100:101], v[252:253]
	v_pk_add_f32 v[102:103], v[102:103], v[254:255]
	v_cvt_pk_bf16_f32 v148, v100, v101
	v_cvt_pk_bf16_f32 v149, v102, v103
	v_lshlrev_b32_e32 v252, 16, v148
	v_and_b32_e32 v253, 0xffff0000, v148
	v_lshlrev_b32_e32 v254, 16, v149
	v_and_b32_e32 v255, 0xffff0000, v149
	v_pk_add_f32 v[100:101], v[100:101], v[252:253] neg_lo:[0,1] neg_hi:[0,1]
	v_pk_add_f32 v[102:103], v[102:103], v[254:255] neg_lo:[0,1] neg_hi:[0,1]
	v_cvt_pk_bf16_f32 v150, v100, v101
	v_cvt_pk_bf16_f32 v151, v102, v103
	global_store_dwordx2 v242, v[148:149], s[44:45] offset:64
	global_store_dwordx2 v242, v[150:151], s[50:51] offset:64
	global_load_dwordx2 v[148:149], v243, s[44:45] offset:96
	global_load_dwordx2 v[150:151], v243, s[50:51] offset:96
	ds_bpermute_b32 v116, v15, v116
	ds_bpermute_b32 v117, v15, v117
	ds_bpermute_b32 v118, v15, v118
	ds_bpermute_b32 v119, v15, v119
	s_waitcnt vmcnt(14)
; __device__ __forceinline__ float bflo(unsigned v) { return __uint_as_float(v << 16); }
; __device__ __forceinline__ float bfhi(unsigned v) { return __uint_as_float(v & 0xffff0000u); }
; template <int EPI, int TI>
; __device__ __forceinline__ void gemm_epilogue(const WS& ws, const f32x4 (&acc)[4][TI], const float (&rs)[TI], int tok0, int n0,
;                                               int wm, int wn, int lr, int lq, bool dry) {
;     ...
;   } else {
; #pragma unroll
;     for (int ni = 0; ni < 4; ++ni)
; #pragma unroll
;       for (int ti = 0; ti < TI; ++ti) {
;         if (!(ti < 4 || (lr == 0 && (ni >> 1) == wn))) continue;
;         const size_t off = (size_t)(ti < 4 ? tokr(ti) : tok0 + 128) * 1024 + nw + ni * 16 + 4 * lq;
;         const u32x2 hi = *(const u32x2*)(ws.HHI + off), lo = *(const u32x2*)(ws.HLO + off);
;         const float h0 = bflo(hi.x) + bflo(lo.x) + acc[ni][ti][0], h1 = bfhi(hi.x) + bfhi(lo.x) + acc[ni][ti][1];
;         const float h2 = bflo(hi.y) + bflo(lo.y) + acc[ni][ti][2], h3 = bfhi(hi.y) + bfhi(lo.y) + acc[ni][ti][3];
;         u32x2 nh; nh.x = cvt_pk_bf16(h0, h1); nh.y = cvt_pk_bf16(h2, h3);
;         u32x2 nl; nl.x = cvt_pk_bf16(h0 - bflo(nh.x), h1 - bfhi(nh.x)); nl.y = cvt_pk_bf16(h2 - bflo(nh.y), h3 - bfhi(nh.y));
;         if (!dry) { *(u32x2*)(ws.HHI + off) = nh; *(u32x2*)(ws.HLO + off) = nl; }
;       }
	s_waitcnt lgkmcnt(8)
	v_lshlrev_b32_e32 v252, 16, v152
	v_and_b32_e32 v253, 0xffff0000, v152
	v_lshlrev_b32_e32 v160, 16, v154
	v_and_b32_e32 v161, 0xffff0000, v154
	v_lshlrev_b32_e32 v254, 16, v153
	v_and_b32_e32 v255, 0xffff0000, v153
	v_lshlrev_b32_e32 v162, 16, v155
	v_and_b32_e32 v163, 0xffff0000, v155
	v_pk_add_f32 v[252:253], v[252:253], v[160:161]
	v_pk_add_f32 v[254:255], v[254:255], v[162:163]
	v_pk_add_f32 v[80:81], v[80:81], v[252:253]
	v_pk_add_f32 v[82:83], v[82:83], v[254:255]
	v_cvt_pk_bf16_f32 v152, v80, v81
	v_cvt_pk_bf16_f32 v153, v82, v83
	v_lshlrev_b32_e32 v252, 16, v152
	v_and_b32_e32 v253, 0xffff0000, v152
	v_lshlrev_b32_e32 v254, 16, v153
	v_and_b32_e32 v255, 0xffff0000, v153
	v_pk_add_f32 v[80:81], v[80:81], v[252:253] neg_lo:[0,1] neg_hi:[0,1]
	v_pk_add_f32 v[82:83], v[82:83], v[254:255] neg_lo:[0,1] neg_hi:[0,1]
	v_cvt_pk_bf16_f32 v154, v80, v81
	v_cvt_pk_bf16_f32 v155, v82, v83
	global_store_dwordx2 v242, v[152:153], s[44:45] offset:96
	global_store_dwordx2 v242, v[154:155], s[50:51] offset:96
	global_load_dwordx2 v[152:153], v244, s[44:45]
	global_load_dwordx2 v[154:155], v244, s[50:51]
	ds_bpermute_b32 v96, v15, v96
	ds_bpermute_b32 v97, v15, v97
	ds_bpermute_b32 v98, v15, v98
	ds_bpermute_b32 v99, v15, v99
	s_waitcnt vmcnt(16)
	s_waitcnt lgkmcnt(8)
	v_lshlrev_b32_e32 v252, 16, v156
	v_and_b32_e32 v253, 0xffff0000, v156
	v_lshlrev_b32_e32 v160, 16, v158
	v_and_b32_e32 v161, 0xffff0000, v158
	v_lshlrev_b32_e32 v254, 16, v157
	v_and_b32_e32 v255, 0xffff0000, v157
	v_lshlrev_b32_e32 v162, 16, v159
	v_and_b32_e32 v163, 0xffff0000, v159
	v_pk_add_f32 v[252:253], v[252:253], v[160:161]
	v_pk_add_f32 v[254:255], v[254:255], v[162:163]
	v_pk_add_f32 v[132:133], v[132:133], v[252:253]
	v_pk_add_f32 v[134:135], v[134:135], v[254:255]
	v_cvt_pk_bf16_f32 v156, v132, v133
	v_cvt_pk_bf16_f32 v157, v134, v135
	v_lshlrev_b32_e32 v252, 16, v156
	v_and_b32_e32 v253, 0xffff0000, v156
	v_lshlrev_b32_e32 v254, 16, v157
	v_and_b32_e32 v255, 0xffff0000, v157
	v_pk_add_f32 v[132:133], v[132:133], v[252:253] neg_lo:[0,1] neg_hi:[0,1]
	v_pk_add_f32 v[134:135], v[134:135], v[254:255] neg_lo:[0,1] neg_hi:[0,1]
	v_cvt_pk_bf16_f32 v158, v132, v133
	v_cvt_pk_bf16_f32 v159, v134, v135
	global_store_dwordx2 v243, v[156:157], s[44:45]
	global_store_dwordx2 v243, v[158:159], s[50:51]
	global_load_dwordx2 v[156:157], v244, s[44:45] offset:32
	global_load_dwordx2 v[158:159], v244, s[50:51] offset:32
	ds_bpermute_b32 v76, v15, v76
	ds_bpermute_b32 v77, v15, v77
	ds_bpermute_b32 v78, v15, v78
	ds_bpermute_b32 v79, v15, v79
	s_waitcnt vmcnt(16)
	s_waitcnt lgkmcnt(8)
	v_lshlrev_b32_e32 v252, 16, v140
	v_and_b32_e32 v253, 0xffff0000, v140
	v_lshlrev_b32_e32 v160, 16, v142
	v_and_b32_e32 v161, 0xffff0000, v142
	v_lshlrev_b32_e32 v254, 16, v141
	v_and_b32_e32 v255, 0xffff0000, v141
	v_lshlrev_b32_e32 v162, 16, v143
	v_and_b32_e32 v163, 0xffff0000, v143
	v_pk_add_f32 v[252:253], v[252:253], v[160:161]
	v_pk_add_f32 v[254:255], v[254:255], v[162:163]
	v_pk_add_f32 v[116:117], v[116:117], v[252:253]
	v_pk_add_f32 v[118:119], v[118:119], v[254:255]
	v_cvt_pk_bf16_f32 v140, v116, v117
	v_cvt_pk_bf16_f32 v141, v118, v119
	v_lshlrev_b32_e32 v252, 16, v140
	v_and_b32_e32 v253, 0xffff0000, v140
	v_lshlrev_b32_e32 v254, 16, v141
	v_and_b32_e32 v255, 0xffff0000, v141
	v_pk_add_f32 v[116:117], v[116:117], v[252:253] neg_lo:[0,1] neg_hi:[0,1]
	v_pk_add_f32 v[118:119], v[118:119], v[254:255] neg_lo:[0,1] neg_hi:[0,1]
	v_cvt_pk_bf16_f32 v142, v116, v117
	v_cvt_pk_bf16_f32 v143, v118, v119
	global_store_dwordx2 v243, v[140:141], s[44:45] offset:32
	global_store_dwordx2 v243, v[142:143], s[50:51] offset:32
	global_load_dwordx2 v[140:141], v244, s[44:45] offset:64
	global_load_dwordx2 v[142:143], v244, s[50:51] offset:64
	ds_bpermute_b32 v128, v15, v128
	ds_bpermute_b32 v129, v15, v129
	ds_bpermute_b32 v130, v15, v130
	ds_bpermute_b32 v131, v15, v131
	s_waitcnt vmcnt(16)
	s_waitcnt lgkmcnt(8)
	v_lshlrev_b32_e32 v252, 16, v144
	v_and_b32_e32 v253, 0xffff0000, v144
	v_lshlrev_b32_e32 v160, 16, v146
	v_and_b32_e32 v161, 0xffff0000, v146
	v_lshlrev_b32_e32 v254, 16, v145
	v_and_b32_e32 v255, 0xffff0000, v145
	v_lshlrev_b32_e32 v162, 16, v147
	v_and_b32_e32 v163, 0xffff0000, v147
	v_pk_add_f32 v[252:253], v[252:253], v[160:161]
	v_pk_add_f32 v[254:255], v[254:255], v[162:163]
	v_pk_add_f32 v[96:97], v[96:97], v[252:253]
	v_pk_add_f32 v[98:99], v[98:99], v[254:255]
	v_cvt_pk_bf16_f32 v144, v96, v97
	v_cvt_pk_bf16_f32 v145, v98, v99
	v_lshlrev_b32_e32 v252, 16, v144
	v_and_b32_e32 v253, 0xffff0000, v144
	v_lshlrev_b32_e32 v254, 16, v145
	v_and_b32_e32 v255, 0xffff0000, v145
	v_pk_add_f32 v[96:97], v[96:97], v[252:253] neg_lo:[0,1] neg_hi:[0,1]
	v_pk_add_f32 v[98:99], v[98:99], v[254:255] neg_lo:[0,1] neg_hi:[0,1]
	v_cvt_pk_bf16_f32 v146, v96, v97
	v_cvt_pk_bf16_f32 v147, v98, v99
	global_store_dwordx2 v243, v[144:145], s[44:45] offset:64
	global_store_dwordx2 v243, v[146:147], s[50:51] offset:64
	global_load_dwordx2 v[144:145], v244, s[44:45] offset:96
	global_load_dwordx2 v[146:147], v244, s[50:51] offset:96
	ds_bpermute_b32 v112, v15, v112
	ds_bpermute_b32 v113, v15, v113
	ds_bpermute_b32 v114, v15, v114
	ds_bpermute_b32 v115, v15, v115
	s_waitcnt vmcnt(16)
	s_waitcnt lgkmcnt(8)
; __device__ __forceinline__ float bflo(unsigned v) { return __uint_as_float(v << 16); }
; __device__ __forceinline__ float bfhi(unsigned v) { return __uint_as_float(v & 0xffff0000u); }
; template <int EPI, int TI>
; __device__ __forceinline__ void gemm_epilogue(const WS& ws, const f32x4 (&acc)[4][TI], const float (&rs)[TI], int tok0, int n0,
;                                               int wm, int wn, int lr, int lq, bool dry) {
;     ...
;   } else {
; #pragma unroll
;     for (int ni = 0; ni < 4; ++ni)
; #pragma unroll
;       for (int ti = 0; ti < TI; ++ti) {
;         if (!(ti < 4 || (lr == 0 && (ni >> 1) == wn))) continue;
;         const size_t off = (size_t)(ti < 4 ? tokr(ti) : tok0 + 128) * 1024 + nw + ni * 16 + 4 * lq;
;         const u32x2 hi = *(const u32x2*)(ws.HHI + off), lo = *(const u32x2*)(ws.HLO + off);
;         const float h0 = bflo(hi.x) + bflo(lo.x) + acc[ni][ti][0], h1 = bfhi(hi.x) + bfhi(lo.x) + acc[ni][ti][1];
;         const float h2 = bflo(hi.y) + bflo(lo.y) + acc[ni][ti][2], h3 = bfhi(hi.y) + bfhi(lo.y) + acc[ni][ti][3];
;         u32x2 nh; nh.x = cvt_pk_bf16(h0, h1); nh.y = cvt_pk_bf16(h2, h3);
;         u32x2 nl; nl.x = cvt_pk_bf16(h0 - bflo(nh.x), h1 - bfhi(nh.x)); nl.y = cvt_pk_bf16(h2 - bflo(nh.y), h3 - bfhi(nh.y));
;         if (!dry) { *(u32x2*)(ws.HHI + off) = nh; *(u32x2*)(ws.HLO + off) = nl; }
;       }
	v_lshlrev_b32_e32 v252, 16, v148
	v_and_b32_e32 v253, 0xffff0000, v148
	v_lshlrev_b32_e32 v160, 16, v150
	v_and_b32_e32 v161, 0xffff0000, v150
	v_lshlrev_b32_e32 v254, 16, v149
	v_and_b32_e32 v255, 0xffff0000, v149
	v_lshlrev_b32_e32 v162, 16, v151
	v_and_b32_e32 v163, 0xffff0000, v151
	v_pk_add_f32 v[252:253], v[252:253], v[160:161]
	v_pk_add_f32 v[254:255], v[254:255], v[162:163]
	v_pk_add_f32 v[76:77], v[76:77], v[252:253]
	v_pk_add_f32 v[78:79], v[78:79], v[254:255]
	v_cvt_pk_bf16_f32 v148, v76, v77
	v_cvt_pk_bf16_f32 v149, v78, v79
	v_lshlrev_b32_e32 v252, 16, v148
	v_and_b32_e32 v253, 0xffff0000, v148
	v_lshlrev_b32_e32 v254, 16, v149
	v_and_b32_e32 v255, 0xffff0000, v149
	v_pk_add_f32 v[76:77], v[76:77], v[252:253] neg_lo:[0,1] neg_hi:[0,1]
	v_pk_add_f32 v[78:79], v[78:79], v[254:255] neg_lo:[0,1] neg_hi:[0,1]
	v_cvt_pk_bf16_f32 v150, v76, v77
	v_cvt_pk_bf16_f32 v151, v78, v79
	global_store_dwordx2 v243, v[148:149], s[44:45] offset:96
	global_store_dwordx2 v243, v[150:151], s[50:51] offset:96
	global_load_dwordx2 v[148:149], v245, s[44:45]
	global_load_dwordx2 v[150:151], v245, s[50:51]
	ds_bpermute_b32 v92, v15, v92
	ds_bpermute_b32 v93, v15, v93
	ds_bpermute_b32 v94, v15, v94
	ds_bpermute_b32 v95, v15, v95
	s_waitcnt vmcnt(16)
	s_waitcnt lgkmcnt(8)
	v_lshlrev_b32_e32 v252, 16, v152
	v_and_b32_e32 v253, 0xffff0000, v152
	v_lshlrev_b32_e32 v160, 16, v154
	v_and_b32_e32 v161, 0xffff0000, v154
	v_lshlrev_b32_e32 v254, 16, v153
	v_and_b32_e32 v255, 0xffff0000, v153
	v_lshlrev_b32_e32 v162, 16, v155
	v_and_b32_e32 v163, 0xffff0000, v155
	v_pk_add_f32 v[252:253], v[252:253], v[160:161]
	v_pk_add_f32 v[254:255], v[254:255], v[162:163]
	v_pk_add_f32 v[128:129], v[128:129], v[252:253]
	v_pk_add_f32 v[130:131], v[130:131], v[254:255]
	v_cvt_pk_bf16_f32 v152, v128, v129
	v_cvt_pk_bf16_f32 v153, v130, v131
	v_lshlrev_b32_e32 v252, 16, v152
	v_and_b32_e32 v253, 0xffff0000, v152
	v_lshlrev_b32_e32 v254, 16, v153
	v_and_b32_e32 v255, 0xffff0000, v153
	v_pk_add_f32 v[128:129], v[128:129], v[252:253] neg_lo:[0,1] neg_hi:[0,1]
	v_pk_add_f32 v[130:131], v[130:131], v[254:255] neg_lo:[0,1] neg_hi:[0,1]
	v_cvt_pk_bf16_f32 v154, v128, v129
	v_cvt_pk_bf16_f32 v155, v130, v131
	global_store_dwordx2 v244, v[152:153], s[44:45]
	global_store_dwordx2 v244, v[154:155], s[50:51]
	global_load_dwordx2 v[152:153], v245, s[44:45] offset:32
	global_load_dwordx2 v[154:155], v245, s[50:51] offset:32
	ds_bpermute_b32 v72, v15, v72
	ds_bpermute_b32 v73, v15, v73
	ds_bpermute_b32 v74, v15, v74
	ds_bpermute_b32 v75, v15, v75
	s_waitcnt vmcnt(16)
	s_waitcnt lgkmcnt(8)
	v_lshlrev_b32_e32 v252, 16, v156
	v_and_b32_e32 v253, 0xffff0000, v156
	v_lshlrev_b32_e32 v160, 16, v158
	v_and_b32_e32 v161, 0xffff0000, v158
	v_lshlrev_b32_e32 v254, 16, v157
	v_and_b32_e32 v255, 0xffff0000, v157
	v_lshlrev_b32_e32 v162, 16, v159
	v_and_b32_e32 v163, 0xffff0000, v159
	v_pk_add_f32 v[252:253], v[252:253], v[160:161]
	v_pk_add_f32 v[254:255], v[254:255], v[162:163]
	v_pk_add_f32 v[112:113], v[112:113], v[252:253]
	v_pk_add_f32 v[114:115], v[114:115], v[254:255]
	v_cvt_pk_bf16_f32 v156, v112, v113
	v_cvt_pk_bf16_f32 v157, v114, v115
	v_lshlrev_b32_e32 v252, 16, v156
	v_and_b32_e32 v253, 0xffff0000, v156
	v_lshlrev_b32_e32 v254, 16, v157
	v_and_b32_e32 v255, 0xffff0000, v157
	v_pk_add_f32 v[112:113], v[112:113], v[252:253] neg_lo:[0,1] neg_hi:[0,1]
	v_pk_add_f32 v[114:115], v[114:115], v[254:255] neg_lo:[0,1] neg_hi:[0,1]
	v_cvt_pk_bf16_f32 v158, v112, v113
	v_cvt_pk_bf16_f32 v159, v114, v115
	global_store_dwordx2 v244, v[156:157], s[44:45] offset:32
	global_store_dwordx2 v244, v[158:159], s[50:51] offset:32
	global_load_dwordx2 v[156:157], v245, s[44:45] offset:64
	global_load_dwordx2 v[158:159], v245, s[50:51] offset:64
	ds_bpermute_b32 v124, v15, v124
	ds_bpermute_b32 v125, v15, v125
	ds_bpermute_b32 v126, v15, v126
	ds_bpermute_b32 v127, v15, v127
	s_waitcnt vmcnt(16)
	s_waitcnt lgkmcnt(8)
	v_lshlrev_b32_e32 v252, 16, v140
	v_and_b32_e32 v253, 0xffff0000, v140
	v_lshlrev_b32_e32 v160, 16, v142
	v_and_b32_e32 v161, 0xffff0000, v142
	v_lshlrev_b32_e32 v254, 16, v141
	v_and_b32_e32 v255, 0xffff0000, v141
	v_lshlrev_b32_e32 v162, 16, v143
	v_and_b32_e32 v163, 0xffff0000, v143
	v_pk_add_f32 v[252:253], v[252:253], v[160:161]
	v_pk_add_f32 v[254:255], v[254:255], v[162:163]
	v_pk_add_f32 v[92:93], v[92:93], v[252:253]
	v_pk_add_f32 v[94:95], v[94:95], v[254:255]
	v_cvt_pk_bf16_f32 v140, v92, v93
	v_cvt_pk_bf16_f32 v141, v94, v95
	v_lshlrev_b32_e32 v252, 16, v140
	v_and_b32_e32 v253, 0xffff0000, v140
	v_lshlrev_b32_e32 v254, 16, v141
	v_and_b32_e32 v255, 0xffff0000, v141
	v_pk_add_f32 v[92:93], v[92:93], v[252:253] neg_lo:[0,1] neg_hi:[0,1]
	v_pk_add_f32 v[94:95], v[94:95], v[254:255] neg_lo:[0,1] neg_hi:[0,1]
	v_cvt_pk_bf16_f32 v142, v92, v93
	v_cvt_pk_bf16_f32 v143, v94, v95
	global_store_dwordx2 v244, v[140:141], s[44:45] offset:64
	global_store_dwordx2 v244, v[142:143], s[50:51] offset:64
	global_load_dwordx2 v[140:141], v245, s[44:45] offset:96
	global_load_dwordx2 v[142:143], v245, s[50:51] offset:96
	ds_bpermute_b32 v104, v15, v104
	ds_bpermute_b32 v105, v15, v105
	ds_bpermute_b32 v106, v15, v106
	ds_bpermute_b32 v107, v15, v107
	s_waitcnt vmcnt(16)
	s_waitcnt lgkmcnt(8)
; __device__ __forceinline__ float bflo(unsigned v) { return __uint_as_float(v << 16); }
; __device__ __forceinline__ float bfhi(unsigned v) { return __uint_as_float(v & 0xffff0000u); }
; template <int EPI, int TI>
; __device__ __forceinline__ void gemm_epilogue(const WS& ws, const f32x4 (&acc)[4][TI], const float (&rs)[TI], int tok0, int n0,
;                                               int wm, int wn, int lr, int lq, bool dry) {
;     ...
;   } else {
; #pragma unroll
;     for (int ni = 0; ni < 4; ++ni)
; #pragma unroll
;       for (int ti = 0; ti < TI; ++ti) {
;         if (!(ti < 4 || (lr == 0 && (ni >> 1) == wn))) continue;
;         const size_t off = (size_t)(ti < 4 ? tokr(ti) : tok0 + 128) * 1024 + nw + ni * 16 + 4 * lq;
;         const u32x2 hi = *(const u32x2*)(ws.HHI + off), lo = *(const u32x2*)(ws.HLO + off);
;         const float h0 = bflo(hi.x) + bflo(lo.x) + acc[ni][ti][0], h1 = bfhi(hi.x) + bfhi(lo.x) + acc[ni][ti][1];
;         const float h2 = bflo(hi.y) + bflo(lo.y) + acc[ni][ti][2], h3 = bfhi(hi.y) + bfhi(lo.y) + acc[ni][ti][3];
;         u32x2 nh; nh.x = cvt_pk_bf16(h0, h1); nh.y = cvt_pk_bf16(h2, h3);
;         u32x2 nl; nl.x = cvt_pk_bf16(h0 - bflo(nh.x), h1 - bfhi(nh.x)); nl.y = cvt_pk_bf16(h2 - bflo(nh.y), h3 - bfhi(nh.y));
;         if (!dry) { *(u32x2*)(ws.HHI + off) = nh; *(u32x2*)(ws.HLO + off) = nl; }
;       }
	v_lshlrev_b32_e32 v252, 16, v144
	v_and_b32_e32 v253, 0xffff0000, v144
	v_lshlrev_b32_e32 v160, 16, v146
	v_and_b32_e32 v161, 0xffff0000, v146
	v_lshlrev_b32_e32 v254, 16, v145
	v_and_b32_e32 v255, 0xffff0000, v145
	v_lshlrev_b32_e32 v162, 16, v147
	v_and_b32_e32 v163, 0xffff0000, v147
	v_pk_add_f32 v[252:253], v[252:253], v[160:161]
	v_pk_add_f32 v[254:255], v[254:255], v[162:163]
	v_pk_add_f32 v[72:73], v[72:73], v[252:253]
	v_pk_add_f32 v[74:75], v[74:75], v[254:255]
	v_cvt_pk_bf16_f32 v144, v72, v73
	v_cvt_pk_bf16_f32 v145, v74, v75
	v_lshlrev_b32_e32 v252, 16, v144
	v_and_b32_e32 v253, 0xffff0000, v144
	v_lshlrev_b32_e32 v254, 16, v145
	v_and_b32_e32 v255, 0xffff0000, v145
	v_pk_add_f32 v[72:73], v[72:73], v[252:253] neg_lo:[0,1] neg_hi:[0,1]
	v_pk_add_f32 v[74:75], v[74:75], v[254:255] neg_lo:[0,1] neg_hi:[0,1]
	v_cvt_pk_bf16_f32 v146, v72, v73
	v_cvt_pk_bf16_f32 v147, v74, v75
	global_store_dwordx2 v244, v[144:145], s[44:45] offset:96
	global_store_dwordx2 v244, v[146:147], s[50:51] offset:96
	ds_bpermute_b32 v84, v15, v84
	ds_bpermute_b32 v85, v15, v85
	ds_bpermute_b32 v86, v15, v86
	ds_bpermute_b32 v87, v15, v87
	s_waitcnt vmcnt(14)
	s_waitcnt lgkmcnt(8)
	v_lshlrev_b32_e32 v252, 16, v148
	v_and_b32_e32 v253, 0xffff0000, v148
	v_lshlrev_b32_e32 v160, 16, v150
	v_and_b32_e32 v161, 0xffff0000, v150
	v_lshlrev_b32_e32 v254, 16, v149
	v_and_b32_e32 v255, 0xffff0000, v149
	v_lshlrev_b32_e32 v162, 16, v151
	v_and_b32_e32 v163, 0xffff0000, v151
	v_pk_add_f32 v[252:253], v[252:253], v[160:161]
	v_pk_add_f32 v[254:255], v[254:255], v[162:163]
	v_pk_add_f32 v[124:125], v[124:125], v[252:253]
	v_pk_add_f32 v[126:127], v[126:127], v[254:255]
	v_cvt_pk_bf16_f32 v148, v124, v125
	v_cvt_pk_bf16_f32 v149, v126, v127
	v_lshlrev_b32_e32 v252, 16, v148
	v_and_b32_e32 v253, 0xffff0000, v148
	v_lshlrev_b32_e32 v254, 16, v149
	v_and_b32_e32 v255, 0xffff0000, v149
	v_pk_add_f32 v[124:125], v[124:125], v[252:253] neg_lo:[0,1] neg_hi:[0,1]
	v_pk_add_f32 v[126:127], v[126:127], v[254:255] neg_lo:[0,1] neg_hi:[0,1]
	v_cvt_pk_bf16_f32 v150, v124, v125
	v_cvt_pk_bf16_f32 v151, v126, v127
	global_store_dwordx2 v245, v[148:149], s[44:45]
	global_store_dwordx2 v245, v[150:151], s[50:51]
	ds_bpermute_b32 v68, v15, v68
	ds_bpermute_b32 v69, v15, v69
	ds_bpermute_b32 v70, v15, v70
	ds_bpermute_b32 v71, v15, v71
	s_waitcnt vmcnt(12)
	s_waitcnt lgkmcnt(8)
	v_lshlrev_b32_e32 v252, 16, v152
	v_and_b32_e32 v253, 0xffff0000, v152
	v_lshlrev_b32_e32 v160, 16, v154
	v_and_b32_e32 v161, 0xffff0000, v154
	v_lshlrev_b32_e32 v254, 16, v153
	v_and_b32_e32 v255, 0xffff0000, v153
	v_lshlrev_b32_e32 v162, 16, v155
	v_and_b32_e32 v163, 0xffff0000, v155
	v_pk_add_f32 v[252:253], v[252:253], v[160:161]
	v_pk_add_f32 v[254:255], v[254:255], v[162:163]
	v_pk_add_f32 v[104:105], v[104:105], v[252:253]
	v_pk_add_f32 v[106:107], v[106:107], v[254:255]
	v_cvt_pk_bf16_f32 v152, v104, v105
	v_cvt_pk_bf16_f32 v153, v106, v107
	v_lshlrev_b32_e32 v252, 16, v152
	v_and_b32_e32 v253, 0xffff0000, v152
	v_lshlrev_b32_e32 v254, 16, v153
	v_and_b32_e32 v255, 0xffff0000, v153
	v_pk_add_f32 v[104:105], v[104:105], v[252:253] neg_lo:[0,1] neg_hi:[0,1]
	v_pk_add_f32 v[106:107], v[106:107], v[254:255] neg_lo:[0,1] neg_hi:[0,1]
	v_cvt_pk_bf16_f32 v154, v104, v105
	v_cvt_pk_bf16_f32 v155, v106, v107
	global_store_dwordx2 v245, v[152:153], s[44:45] offset:32
	global_store_dwordx2 v245, v[154:155], s[50:51] offset:32
	s_waitcnt vmcnt(10)
	s_waitcnt lgkmcnt(4)
	v_lshlrev_b32_e32 v252, 16, v156
	v_and_b32_e32 v253, 0xffff0000, v156
	v_lshlrev_b32_e32 v160, 16, v158
	v_and_b32_e32 v161, 0xffff0000, v158
	v_lshlrev_b32_e32 v254, 16, v157
	v_and_b32_e32 v255, 0xffff0000, v157
	v_lshlrev_b32_e32 v162, 16, v159
	v_and_b32_e32 v163, 0xffff0000, v159
	v_pk_add_f32 v[252:253], v[252:253], v[160:161]
	v_pk_add_f32 v[254:255], v[254:255], v[162:163]
	v_pk_add_f32 v[84:85], v[84:85], v[252:253]
	v_pk_add_f32 v[86:87], v[86:87], v[254:255]
	v_cvt_pk_bf16_f32 v156, v84, v85
	v_cvt_pk_bf16_f32 v157, v86, v87
	v_lshlrev_b32_e32 v252, 16, v156
	v_and_b32_e32 v253, 0xffff0000, v156
	v_lshlrev_b32_e32 v254, 16, v157
	v_and_b32_e32 v255, 0xffff0000, v157
	v_pk_add_f32 v[84:85], v[84:85], v[252:253] neg_lo:[0,1] neg_hi:[0,1]
	v_pk_add_f32 v[86:87], v[86:87], v[254:255] neg_lo:[0,1] neg_hi:[0,1]
	v_cvt_pk_bf16_f32 v158, v84, v85
	v_cvt_pk_bf16_f32 v159, v86, v87
	global_store_dwordx2 v245, v[156:157], s[44:45] offset:64
	global_store_dwordx2 v245, v[158:159], s[50:51] offset:64
	s_waitcnt vmcnt(8)
	s_waitcnt lgkmcnt(0)
; __device__ __forceinline__ float bflo(unsigned v) { return __uint_as_float(v << 16); }
; __device__ __forceinline__ float bfhi(unsigned v) { return __uint_as_float(v & 0xffff0000u); }
; template <int EPI, int TI>
; __device__ __forceinline__ void gemm_epilogue(const WS& ws, const f32x4 (&acc)[4][TI], const float (&rs)[TI], int tok0, int n0,
;                                               int wm, int wn, int lr, int lq, bool dry) {
;     ...
;   } else {
; #pragma unroll
;     for (int ni = 0; ni < 4; ++ni)
; #pragma unroll
;       for (int ti = 0; ti < TI; ++ti) {
;         if (!(ti < 4 || (lr == 0 && (ni >> 1) == wn))) continue;
;         const size_t off = (size_t)(ti < 4 ? tokr(ti) : tok0 + 128) * 1024 + nw + ni * 16 + 4 * lq;
;         const u32x2 hi = *(const u32x2*)(ws.HHI + off), lo = *(const u32x2*)(ws.HLO + off);
;         const float h0 = bflo(hi.x) + bflo(lo.x) + acc[ni][ti][0], h1 = bfhi(hi.x) + bfhi(lo.x) + acc[ni][ti][1];
;         const float h2 = bflo(hi.y) + bflo(lo.y) + acc[ni][ti][2], h3 = bfhi(hi.y) + bfhi(lo.y) + acc[ni][ti][3];
;         u32x2 nh; nh.x = cvt_pk_bf16(h0, h1); nh.y = cvt_pk_bf16(h2, h3);
;         u32x2 nl; nl.x = cvt_pk_bf16(h0 - bflo(nh.x), h1 - bfhi(nh.x)); nl.y = cvt_pk_bf16(h2 - bflo(nh.y), h3 - bfhi(nh.y));
;         if (!dry) { *(u32x2*)(ws.HHI + off) = nh; *(u32x2*)(ws.HLO + off) = nl; }
;       }
	v_lshlrev_b32_e32 v252, 16, v140
	v_and_b32_e32 v253, 0xffff0000, v140
	v_lshlrev_b32_e32 v160, 16, v142
	v_and_b32_e32 v161, 0xffff0000, v142
	v_lshlrev_b32_e32 v254, 16, v141
	v_and_b32_e32 v255, 0xffff0000, v141
	v_lshlrev_b32_e32 v162, 16, v143
	v_and_b32_e32 v163, 0xffff0000, v143
	v_pk_add_f32 v[252:253], v[252:253], v[160:161]
	v_pk_add_f32 v[254:255], v[254:255], v[162:163]
	v_pk_add_f32 v[68:69], v[68:69], v[252:253]
	v_pk_add_f32 v[70:71], v[70:71], v[254:255]
	v_cvt_pk_bf16_f32 v140, v68, v69
	v_cvt_pk_bf16_f32 v141, v70, v71
	v_lshlrev_b32_e32 v252, 16, v140
	v_and_b32_e32 v253, 0xffff0000, v140
	v_lshlrev_b32_e32 v254, 16, v141
	v_and_b32_e32 v255, 0xffff0000, v141
	v_pk_add_f32 v[68:69], v[68:69], v[252:253] neg_lo:[0,1] neg_hi:[0,1]
	v_pk_add_f32 v[70:71], v[70:71], v[254:255] neg_lo:[0,1] neg_hi:[0,1]
	v_cvt_pk_bf16_f32 v142, v68, v69
	v_cvt_pk_bf16_f32 v143, v70, v71
	global_store_dwordx2 v245, v[140:141], s[44:45] offset:96
	global_store_dwordx2 v245, v[142:143], s[50:51] offset:96
	s_and_b64 exec, s[6:7], s[42:43]
	s_waitcnt vmcnt(63)
	v_lshlrev_b32_e32 v252, 16, v204
	v_and_b32_e32 v253, 0xffff0000, v204
	v_lshlrev_b32_e32 v160, 16, v206
	v_and_b32_e32 v161, 0xffff0000, v206
	v_lshlrev_b32_e32 v254, 16, v205
	v_and_b32_e32 v255, 0xffff0000, v205
	v_lshlrev_b32_e32 v162, 16, v207
	v_and_b32_e32 v163, 0xffff0000, v207
	v_pk_add_f32 v[252:253], v[252:253], v[160:161]
	v_pk_add_f32 v[254:255], v[254:255], v[162:163]
	v_pk_add_f32 v[108:109], v[108:109], v[252:253]
	v_pk_add_f32 v[110:111], v[110:111], v[254:255]
	v_cvt_pk_bf16_f32 v204, v108, v109
	v_cvt_pk_bf16_f32 v205, v110, v111
	v_lshlrev_b32_e32 v252, 16, v204
	v_and_b32_e32 v253, 0xffff0000, v204
	v_lshlrev_b32_e32 v254, 16, v205
	v_and_b32_e32 v255, 0xffff0000, v205
	v_pk_add_f32 v[108:109], v[108:109], v[252:253] neg_lo:[0,1] neg_hi:[0,1]
	v_pk_add_f32 v[110:111], v[110:111], v[254:255] neg_lo:[0,1] neg_hi:[0,1]
	v_cvt_pk_bf16_f32 v206, v108, v109
	v_cvt_pk_bf16_f32 v207, v110, v111
	global_store_dwordx2 v246, v[204:205], s[44:45]
	global_store_dwordx2 v246, v[206:207], s[50:51]
	s_waitcnt vmcnt(63)
	v_lshlrev_b32_e32 v252, 16, v208
	v_and_b32_e32 v253, 0xffff0000, v208
	v_lshlrev_b32_e32 v160, 16, v210
	v_and_b32_e32 v161, 0xffff0000, v210
	v_lshlrev_b32_e32 v254, 16, v209
	v_and_b32_e32 v255, 0xffff0000, v209
	v_lshlrev_b32_e32 v162, 16, v211
	v_and_b32_e32 v163, 0xffff0000, v211
	v_pk_add_f32 v[252:253], v[252:253], v[160:161]
	v_pk_add_f32 v[254:255], v[254:255], v[162:163]
	v_pk_add_f32 v[88:89], v[88:89], v[252:253]
	v_pk_add_f32 v[90:91], v[90:91], v[254:255]
	v_cvt_pk_bf16_f32 v208, v88, v89
	v_cvt_pk_bf16_f32 v209, v90, v91
	v_lshlrev_b32_e32 v252, 16, v208
	v_and_b32_e32 v253, 0xffff0000, v208
	v_lshlrev_b32_e32 v254, 16, v209
	v_and_b32_e32 v255, 0xffff0000, v209
	v_pk_add_f32 v[88:89], v[88:89], v[252:253] neg_lo:[0,1] neg_hi:[0,1]
	v_pk_add_f32 v[90:91], v[90:91], v[254:255] neg_lo:[0,1] neg_hi:[0,1]
	v_cvt_pk_bf16_f32 v210, v88, v89
	v_cvt_pk_bf16_f32 v211, v90, v91
	global_store_dwordx2 v246, v[208:209], s[44:45] offset:32
	global_store_dwordx2 v246, v[210:211], s[50:51] offset:32
	s_and_b64 exec, s[6:7], s[52:53]
	s_waitcnt vmcnt(63)
	v_lshlrev_b32_e32 v252, 16, v212
	v_and_b32_e32 v253, 0xffff0000, v212
	v_lshlrev_b32_e32 v160, 16, v214
	v_and_b32_e32 v161, 0xffff0000, v214
	v_lshlrev_b32_e32 v254, 16, v213
	v_and_b32_e32 v255, 0xffff0000, v213
	v_lshlrev_b32_e32 v162, 16, v215
	v_and_b32_e32 v163, 0xffff0000, v215
	v_pk_add_f32 v[252:253], v[252:253], v[160:161]
	v_pk_add_f32 v[254:255], v[254:255], v[162:163]
	v_pk_add_f32 v[36:37], v[36:37], v[252:253]
	v_pk_add_f32 v[38:39], v[38:39], v[254:255]
	v_cvt_pk_bf16_f32 v212, v36, v37
	v_cvt_pk_bf16_f32 v213, v38, v39
	v_lshlrev_b32_e32 v252, 16, v212
	v_and_b32_e32 v253, 0xffff0000, v212
	v_lshlrev_b32_e32 v254, 16, v213
	v_and_b32_e32 v255, 0xffff0000, v213
	v_pk_add_f32 v[36:37], v[36:37], v[252:253] neg_lo:[0,1] neg_hi:[0,1]
	v_pk_add_f32 v[38:39], v[38:39], v[254:255] neg_lo:[0,1] neg_hi:[0,1]
	v_cvt_pk_bf16_f32 v214, v36, v37
	v_cvt_pk_bf16_f32 v215, v38, v39
	global_store_dwordx2 v246, v[212:213], s[44:45] offset:64
	global_store_dwordx2 v246, v[214:215], s[50:51] offset:64
	s_waitcnt vmcnt(63)
	v_lshlrev_b32_e32 v252, 16, v216
	v_and_b32_e32 v253, 0xffff0000, v216
	v_lshlrev_b32_e32 v160, 16, v218
	v_and_b32_e32 v161, 0xffff0000, v218
	v_lshlrev_b32_e32 v254, 16, v217
	v_and_b32_e32 v255, 0xffff0000, v217
	v_lshlrev_b32_e32 v162, 16, v219
	v_and_b32_e32 v163, 0xffff0000, v219
	v_pk_add_f32 v[252:253], v[252:253], v[160:161]
	v_pk_add_f32 v[254:255], v[254:255], v[162:163]
	v_pk_add_f32 v[8:9], v[8:9], v[252:253]
	v_pk_add_f32 v[10:11], v[10:11], v[254:255]
	v_cvt_pk_bf16_f32 v216, v8, v9
	v_cvt_pk_bf16_f32 v217, v10, v11
	v_lshlrev_b32_e32 v252, 16, v216
	v_and_b32_e32 v253, 0xffff0000, v216
	v_lshlrev_b32_e32 v254, 16, v217
	v_and_b32_e32 v255, 0xffff0000, v217
	v_pk_add_f32 v[8:9], v[8:9], v[252:253] neg_lo:[0,1] neg_hi:[0,1]
	v_pk_add_f32 v[10:11], v[10:11], v[254:255] neg_lo:[0,1] neg_hi:[0,1]
	v_cvt_pk_bf16_f32 v218, v8, v9
	v_cvt_pk_bf16_f32 v219, v10, v11
	global_store_dwordx2 v246, v[216:217], s[44:45] offset:96
	global_store_dwordx2 v246, v[218:219], s[50:51] offset:96
	s_mov_b64 exec, s[6:7]

;     ...
;     auto store = [&](const u32x4 (&ra)[4], const u32x4 (&rb)[2], const u32x4& rx, int buf) {
; #pragma unroll
;       for (int i = 0; i < 4; ++i) {
;         if (RS) ss[i] += sumsq8(__builtin_bit_cast(bf16x8, ra[i]));
;         *(u32x4*)(As + buf * ASTG + i * 4096 + soff) = ra[i];
;       }
; #pragma unroll
;       for (int i = 0; i < 2; ++i) *(u32x4*)(Bs + buf * 16384 + i * 8192 + woff) = rb[i];
;       if (TI == 5) {
;         if (RS) ss[4] += sumsq8(__builtin_bit_cast(bf16x8, rx));
;         if (srow == 0) *(u32x4*)(Ax0 + buf * 128 + ((tid & 7) << 4)) = rx;
;       }
.LBB0_1822:
	s_waitcnt vmcnt(15)
	ds_write_b128 v178, v[40:43]
	s_waitcnt vmcnt(14)
	ds_write_b128 v178, v[44:47] offset:4096
	s_waitcnt vmcnt(13)
	ds_write_b128 v178, v[48:51] offset:8192
	s_waitcnt vmcnt(12)
	ds_write_b128 v178, v[52:55] offset:12288
	s_waitcnt vmcnt(11)
	ds_write_b128 v177, v[56:59] offset:32768
	s_waitcnt vmcnt(10)
	ds_write_b128 v177, v[60:63] offset:40960
	s_and_saveexec_b64 s[4:5], s[38:39]
	s_cbranch_execz .LBB0_1779
	s_waitcnt vmcnt(9)
	ds_write_b128 v202, v[64:67]
	s_branch .LBB0_1779
